# row sum of squares in norm0 / layer post phases: DPP row reduction + row_bcast + readlane instead of six bpermute round trips
# baseline (speedup 1.0000x reference)
; DI int osgpr(int v) { asm volatile("" : "+s"(v)); return v; }
; DI float wave_sum(float v) {
; #pragma unroll
;     for (int o = 32; o >= 1; o >>= 1) v += __shfl_xor(v, o);
;     return v;
; DI void norm0_phase(const P& p, unsigned char* smem) {
;     ...
;     for (int rt = osgpr(blockIdx.x); rt < NROW / 16; rt += gridDim.x) {
;       for (int rr = 0; rr < 2; ++rr) {
;         const int row = rt * 16 + wave * 2 + rr;
;         const float* h = row < NLAT ? p.x + (size_t)row * DM : p.ctx + (size_t)(row - NLAT) * DM;
;         const int mr = row < NLAT ? (row >> 11) : 4;
;         f32x4 v[8]; float ss = 0.f;
; #pragma unroll
;         for (int i = 0; i < 8; ++i) { v[i] = __builtin_nontemporal_load((const f32x4*)(h + i * 256 + lane * 4)); ss += v[i][0] * v[i][0] + v[i][1] * v[i][1] + v[i][2] * v[i][2] + v[i][3] * v[i][3]; }
;         ss = wave_sum(ss);
;         const float rstd = rsqrtf(ss * (1.f / 2048.f) + 1e-6f);
;         const float* md = mod + (size_t)mr * 6144;
; #pragma unroll
;         for (int i = 0; i < 8; ++i) {
;             const int j = i * 256 + lane * 4;
;             const f32x4 gw = *(const f32x4*)(p.norm_pre + j), sh = *(const f32x4*)(md + j), scl = *(const f32x4*)(md + 2048 + j);
;             float o[4];
; #pragma unroll
;             for (int e = 0; e < 4; ++e) o[e] = v[i][e] * rstd * gw[e] * (1.f + scl[e]) + sh[e];
;             u32x2 w; w.x = pk2(o[0], o[1]); w.y = pk2(o[2], o[3]);
;             *(u32x2*)(nb + (size_t)row * DM + j) = w;
.LBB0_97:
	s_lshl_b32 s24, s28, 4
	v_add_u32_e32 v79, s24, v69
	v_ashrrev_i32_e32 v0, 11, v79
	v_mul_hi_i32_i24_e32 v61, 0x6000, v0
	v_mul_i32_i24_e32 v60, 0x6000, v0
	s_mov_b64 s[18:19], -1
	v_and_b32_e32 v4, 63, v166
	v_readfirstlane_b32 s20, v69
	v_lshlrev_b32_e32 v0, 4, v4
	v_lshlrev_b32_e32 v2, 3, v4
	v_add_u32_e32 v1, 0x1000, v0
	v_add_u32_e32 v3, 0x1000, v2
	s_add_u32 s20, s24, s20
	s_lshr_b32 s25, s20, 11
	s_cmpk_ge_u32 s20, 0x2000
	s_cselect_b32 s25, 4, s25
	s_mul_i32 s25, s25, 0x6000
	s_add_u32 s22, s8, s25
	s_addc_u32 s23, s9, 0
	s_add_u32 s48, s22, 0x2000
	s_addc_u32 s49, s23, 0
	s_lshl_b32 s25, s20, 12
	s_add_u32 s26, s10, s25
	s_addc_u32 s27, s11, 0
	global_load_dwordx4 v[80:83], v0, s[6:7] offset:0
	global_load_dwordx4 v[84:87], v0, s[6:7] offset:1024
	global_load_dwordx4 v[88:91], v0, s[6:7] offset:2048
	global_load_dwordx4 v[92:95], v0, s[6:7] offset:3072
	global_load_dwordx4 v[96:99], v1, s[6:7] offset:0
	global_load_dwordx4 v[100:103], v1, s[6:7] offset:1024
	global_load_dwordx4 v[104:107], v1, s[6:7] offset:2048
	global_load_dwordx4 v[108:111], v1, s[6:7] offset:3072
	global_load_dwordx4 v[168:171], v0, s[22:23] offset:0
	global_load_dwordx4 v[200:203], v0, s[48:49] offset:0
	global_load_dwordx4 v[172:175], v0, s[22:23] offset:1024
	global_load_dwordx4 v[204:207], v0, s[48:49] offset:1024
	global_load_dwordx4 v[176:179], v0, s[22:23] offset:2048
	global_load_dwordx4 v[208:211], v0, s[48:49] offset:2048
	global_load_dwordx4 v[180:183], v0, s[22:23] offset:3072
	global_load_dwordx4 v[212:215], v0, s[48:49] offset:3072
	global_load_dwordx4 v[184:187], v1, s[22:23] offset:0
	global_load_dwordx4 v[216:219], v1, s[48:49] offset:0
	global_load_dwordx4 v[188:191], v1, s[22:23] offset:1024
	global_load_dwordx4 v[220:223], v1, s[48:49] offset:1024
	global_load_dwordx4 v[192:195], v1, s[22:23] offset:2048
	global_load_dwordx4 v[224:227], v1, s[48:49] offset:2048
	global_load_dwordx4 v[196:199], v1, s[22:23] offset:3072
	global_load_dwordx4 v[228:231], v1, s[48:49] offset:3072
	s_waitcnt vmcnt(24)
	v_mul_f32_e32 v4, v112, v112
	v_mul_f32_e32 v5, v113, v113
	v_fmac_f32_e32 v4, v114, v114
	v_fmac_f32_e32 v5, v115, v115
	v_fmac_f32_e32 v4, v116, v116
	v_fmac_f32_e32 v5, v117, v117
	v_fmac_f32_e32 v4, v118, v118
	v_fmac_f32_e32 v5, v119, v119
	v_fmac_f32_e32 v4, v120, v120
	v_fmac_f32_e32 v5, v121, v121
	v_fmac_f32_e32 v4, v122, v122
	v_fmac_f32_e32 v5, v123, v123
	v_fmac_f32_e32 v4, v124, v124
	v_fmac_f32_e32 v5, v125, v125
	v_fmac_f32_e32 v4, v126, v126
	v_fmac_f32_e32 v5, v127, v127
	v_fmac_f32_e32 v4, v128, v128
	v_fmac_f32_e32 v5, v129, v129
	v_fmac_f32_e32 v4, v130, v130
	v_fmac_f32_e32 v5, v131, v131
	v_fmac_f32_e32 v4, v132, v132
	v_fmac_f32_e32 v5, v133, v133
	v_fmac_f32_e32 v4, v134, v134
	v_fmac_f32_e32 v5, v135, v135
	v_fmac_f32_e32 v4, v136, v136
	v_fmac_f32_e32 v5, v137, v137
	v_fmac_f32_e32 v4, v138, v138
	v_fmac_f32_e32 v5, v139, v139
	v_fmac_f32_e32 v4, v140, v140
	v_fmac_f32_e32 v5, v141, v141
	v_fmac_f32_e32 v4, v142, v142
	v_fmac_f32_e32 v5, v143, v143
	v_add_f32_e32 v4, v4, v5
	v_mul_f32_e32 v6, v144, v144
	v_mul_f32_e32 v7, v145, v145
	v_fmac_f32_e32 v6, v146, v146
	v_fmac_f32_e32 v7, v147, v147
	v_fmac_f32_e32 v6, v148, v148
	v_fmac_f32_e32 v7, v149, v149
	v_fmac_f32_e32 v6, v150, v150
	v_fmac_f32_e32 v7, v151, v151
	v_fmac_f32_e32 v6, v152, v152
	v_fmac_f32_e32 v7, v153, v153
	v_fmac_f32_e32 v6, v154, v154
	v_fmac_f32_e32 v7, v155, v155
	v_fmac_f32_e32 v6, v156, v156
	v_fmac_f32_e32 v7, v157, v157
	v_fmac_f32_e32 v6, v158, v158
	v_fmac_f32_e32 v7, v159, v159
	v_fmac_f32_e32 v6, v160, v160
	v_fmac_f32_e32 v7, v161, v161
	v_fmac_f32_e32 v6, v162, v162
	v_fmac_f32_e32 v7, v163, v163
	v_fmac_f32_e32 v6, v232, v232
	v_fmac_f32_e32 v7, v233, v233
	v_fmac_f32_e32 v6, v234, v234
	v_fmac_f32_e32 v7, v235, v235
	v_fmac_f32_e32 v6, v236, v236
	v_fmac_f32_e32 v7, v237, v237
	v_fmac_f32_e32 v6, v238, v238
	v_fmac_f32_e32 v7, v239, v239
	v_fmac_f32_e32 v6, v240, v240
	v_fmac_f32_e32 v7, v241, v241
	v_fmac_f32_e32 v6, v242, v242
	v_fmac_f32_e32 v7, v243, v243
	v_add_f32_e32 v6, v6, v7
	s_nop 1
	v_add_f32_dpp v4, v4, v4 quad_perm:[1,0,3,2] row_mask:0xf bank_mask:0xf
	v_add_f32_dpp v6, v6, v6 quad_perm:[1,0,3,2] row_mask:0xf bank_mask:0xf
	s_nop 0
	v_add_f32_dpp v4, v4, v4 quad_perm:[2,3,0,1] row_mask:0xf bank_mask:0xf
	v_add_f32_dpp v6, v6, v6 quad_perm:[2,3,0,1] row_mask:0xf bank_mask:0xf
	s_nop 0
	v_add_f32_dpp v4, v4, v4 row_half_mirror row_mask:0xf bank_mask:0xf
	v_add_f32_dpp v6, v6, v6 row_half_mirror row_mask:0xf bank_mask:0xf
	s_nop 0
	v_add_f32_dpp v4, v4, v4 row_mirror row_mask:0xf bank_mask:0xf
	v_add_f32_dpp v6, v6, v6 row_mirror row_mask:0xf bank_mask:0xf
	s_nop 0
	v_add_f32_dpp v4, v4, v4 row_bcast:15 row_mask:0xa bank_mask:0xf
	v_add_f32_dpp v6, v6, v6 row_bcast:15 row_mask:0xa bank_mask:0xf
	s_nop 0
	v_add_f32_dpp v4, v4, v4 row_bcast:31 row_mask:0xc bank_mask:0xf
	v_add_f32_dpp v6, v6, v6 row_bcast:31 row_mask:0xc bank_mask:0xf
	s_nop 0
	v_readlane_b32 s44, v4, 63
	v_readlane_b32 s45, v6, 63
	v_mov_b32_e32 v4, s44
	v_mov_b32_e32 v6, s45
	v_fmamk_f32 v4, v4, 0x3a000000, v78
	v_fmamk_f32 v6, v6, 0x3a000000, v78
	v_rsq_f32_e32 v10, v4
	v_rsq_f32_e32 v11, v6
	s_waitcnt vmcnt(16)
	v_mul_f32_e32 v12, v112, v10
	v_mul_f32_e32 v13, v113, v10
	v_mul_f32_e32 v14, v114, v10
	v_mul_f32_e32 v15, v115, v10
	v_mul_f32_e32 v12, v12, v80
	v_mul_f32_e32 v13, v13, v81
	v_mul_f32_e32 v14, v14, v82
	v_mul_f32_e32 v15, v15, v83
	s_waitcnt vmcnt(14)
; DI void norm0_phase(const P& p, unsigned char* smem) {
;     ...
; #pragma unroll
;         for (int i = 0; i < 8; ++i) {
;             const int j = i * 256 + lane * 4;
;             const f32x4 gw = *(const f32x4*)(p.norm_pre + j), sh = *(const f32x4*)(md + j), scl = *(const f32x4*)(md + 2048 + j);
;             float o[4];
; #pragma unroll
;             for (int e = 0; e < 4; ++e) o[e] = v[i][e] * rstd * gw[e] * (1.f + scl[e]) + sh[e];
;             u32x2 w; w.x = pk2(o[0], o[1]); w.y = pk2(o[2], o[3]);
;             *(u32x2*)(nb + (size_t)row * DM + j) = w;
;         }
	v_add_f32_e32 v16, 1.0, v200
	v_add_f32_e32 v17, 1.0, v201
	v_add_f32_e32 v18, 1.0, v202
	v_add_f32_e32 v19, 1.0, v203
	v_fma_f32 v12, v12, v16, v168
	v_fma_f32 v13, v13, v17, v169
	v_fma_f32 v14, v14, v18, v170
	v_fma_f32 v15, v15, v19, v171
	v_cvt_pk_bf16_f32 v20, v12, v13
	v_cvt_pk_bf16_f32 v21, v14, v15
	global_store_dwordx2 v2, v[20:21], s[26:27] offset:0
	v_mul_f32_e32 v12, v116, v10
	v_mul_f32_e32 v13, v117, v10
	v_mul_f32_e32 v14, v118, v10
	v_mul_f32_e32 v15, v119, v10
	v_mul_f32_e32 v12, v12, v84
	v_mul_f32_e32 v13, v13, v85
	v_mul_f32_e32 v14, v14, v86
	v_mul_f32_e32 v15, v15, v87
	s_waitcnt vmcnt(13)
	v_add_f32_e32 v16, 1.0, v204
	v_add_f32_e32 v17, 1.0, v205
	v_add_f32_e32 v18, 1.0, v206
	v_add_f32_e32 v19, 1.0, v207
	v_fma_f32 v12, v12, v16, v172
	v_fma_f32 v13, v13, v17, v173
	v_fma_f32 v14, v14, v18, v174
	v_fma_f32 v15, v15, v19, v175
	v_cvt_pk_bf16_f32 v22, v12, v13
	v_cvt_pk_bf16_f32 v23, v14, v15
	global_store_dwordx2 v2, v[22:23], s[26:27] offset:512
	v_mul_f32_e32 v12, v120, v10
	v_mul_f32_e32 v13, v121, v10
	v_mul_f32_e32 v14, v122, v10
	v_mul_f32_e32 v15, v123, v10
	v_mul_f32_e32 v12, v12, v88
	v_mul_f32_e32 v13, v13, v89
	v_mul_f32_e32 v14, v14, v90
	v_mul_f32_e32 v15, v15, v91
	s_waitcnt vmcnt(12)
	v_add_f32_e32 v16, 1.0, v208
	v_add_f32_e32 v17, 1.0, v209
	v_add_f32_e32 v18, 1.0, v210
	v_add_f32_e32 v19, 1.0, v211
	v_fma_f32 v12, v12, v16, v176
	v_fma_f32 v13, v13, v17, v177
	v_fma_f32 v14, v14, v18, v178
	v_fma_f32 v15, v15, v19, v179
	v_cvt_pk_bf16_f32 v20, v12, v13
	v_cvt_pk_bf16_f32 v21, v14, v15
	global_store_dwordx2 v2, v[20:21], s[26:27] offset:1024
	v_mul_f32_e32 v12, v124, v10
	v_mul_f32_e32 v13, v125, v10
	v_mul_f32_e32 v14, v126, v10
	v_mul_f32_e32 v15, v127, v10
	v_mul_f32_e32 v12, v12, v92
	v_mul_f32_e32 v13, v13, v93
	v_mul_f32_e32 v14, v14, v94
	v_mul_f32_e32 v15, v15, v95
	s_waitcnt vmcnt(11)
	v_add_f32_e32 v16, 1.0, v212
	v_add_f32_e32 v17, 1.0, v213
	v_add_f32_e32 v18, 1.0, v214
	v_add_f32_e32 v19, 1.0, v215
	v_fma_f32 v12, v12, v16, v180
	v_fma_f32 v13, v13, v17, v181
	v_fma_f32 v14, v14, v18, v182
	v_fma_f32 v15, v15, v19, v183
	v_cvt_pk_bf16_f32 v22, v12, v13
	v_cvt_pk_bf16_f32 v23, v14, v15
	global_store_dwordx2 v2, v[22:23], s[26:27] offset:1536
	v_mul_f32_e32 v12, v128, v10
	v_mul_f32_e32 v13, v129, v10
	v_mul_f32_e32 v14, v130, v10
	v_mul_f32_e32 v15, v131, v10
	v_mul_f32_e32 v12, v12, v96
	v_mul_f32_e32 v13, v13, v97
	v_mul_f32_e32 v14, v14, v98
	v_mul_f32_e32 v15, v15, v99
	s_waitcnt vmcnt(10)
	v_add_f32_e32 v16, 1.0, v216
	v_add_f32_e32 v17, 1.0, v217
	v_add_f32_e32 v18, 1.0, v218
	v_add_f32_e32 v19, 1.0, v219
	v_fma_f32 v12, v12, v16, v184
	v_fma_f32 v13, v13, v17, v185
	v_fma_f32 v14, v14, v18, v186
	v_fma_f32 v15, v15, v19, v187
	v_cvt_pk_bf16_f32 v20, v12, v13
	v_cvt_pk_bf16_f32 v21, v14, v15
	global_store_dwordx2 v2, v[20:21], s[26:27] offset:2048
	v_mul_f32_e32 v12, v132, v10
	v_mul_f32_e32 v13, v133, v10
	v_mul_f32_e32 v14, v134, v10
	v_mul_f32_e32 v15, v135, v10
	v_mul_f32_e32 v12, v12, v100
	v_mul_f32_e32 v13, v13, v101
	v_mul_f32_e32 v14, v14, v102
	v_mul_f32_e32 v15, v15, v103
	s_waitcnt vmcnt(9)
	v_add_f32_e32 v16, 1.0, v220
	v_add_f32_e32 v17, 1.0, v221
	v_add_f32_e32 v18, 1.0, v222
	v_add_f32_e32 v19, 1.0, v223
	v_fma_f32 v12, v12, v16, v188
	v_fma_f32 v13, v13, v17, v189
	v_fma_f32 v14, v14, v18, v190
	v_fma_f32 v15, v15, v19, v191
	v_cvt_pk_bf16_f32 v22, v12, v13
	v_cvt_pk_bf16_f32 v23, v14, v15
	global_store_dwordx2 v2, v[22:23], s[26:27] offset:2560
	v_mul_f32_e32 v12, v136, v10
	v_mul_f32_e32 v13, v137, v10
	v_mul_f32_e32 v14, v138, v10
	v_mul_f32_e32 v15, v139, v10
	v_mul_f32_e32 v12, v12, v104
	v_mul_f32_e32 v13, v13, v105
	v_mul_f32_e32 v14, v14, v106
	v_mul_f32_e32 v15, v15, v107
	s_waitcnt vmcnt(8)
	v_add_f32_e32 v16, 1.0, v224
	v_add_f32_e32 v17, 1.0, v225
	v_add_f32_e32 v18, 1.0, v226
	v_add_f32_e32 v19, 1.0, v227
	v_fma_f32 v12, v12, v16, v192
	v_fma_f32 v13, v13, v17, v193
	v_fma_f32 v14, v14, v18, v194
	v_fma_f32 v15, v15, v19, v195
	v_cvt_pk_bf16_f32 v20, v12, v13
	v_cvt_pk_bf16_f32 v21, v14, v15
	global_store_dwordx2 v2, v[20:21], s[26:27] offset:3072
	v_mul_f32_e32 v12, v140, v10
	v_mul_f32_e32 v13, v141, v10
	v_mul_f32_e32 v14, v142, v10
	v_mul_f32_e32 v15, v143, v10
	v_mul_f32_e32 v12, v12, v108
	v_mul_f32_e32 v13, v13, v109
	v_mul_f32_e32 v14, v14, v110
	v_mul_f32_e32 v15, v15, v111
	s_waitcnt vmcnt(7)
; DI void norm0_phase(const P& p, unsigned char* smem) {
;     ...
; #pragma unroll
;         for (int i = 0; i < 8; ++i) {
;             const int j = i * 256 + lane * 4;
;             const f32x4 gw = *(const f32x4*)(p.norm_pre + j), sh = *(const f32x4*)(md + j), scl = *(const f32x4*)(md + 2048 + j);
;             float o[4];
; #pragma unroll
;             for (int e = 0; e < 4; ++e) o[e] = v[i][e] * rstd * gw[e] * (1.f + scl[e]) + sh[e];
;             u32x2 w; w.x = pk2(o[0], o[1]); w.y = pk2(o[2], o[3]);
;             *(u32x2*)(nb + (size_t)row * DM + j) = w;
;         }
	v_add_f32_e32 v16, 1.0, v228
	v_add_f32_e32 v17, 1.0, v229
	v_add_f32_e32 v18, 1.0, v230
	v_add_f32_e32 v19, 1.0, v231
	v_fma_f32 v12, v12, v16, v196
	v_fma_f32 v13, v13, v17, v197
	v_fma_f32 v14, v14, v18, v198
	v_fma_f32 v15, v15, v19, v199
	v_cvt_pk_bf16_f32 v22, v12, v13
	v_cvt_pk_bf16_f32 v23, v14, v15
	global_store_dwordx2 v2, v[22:23], s[26:27] offset:3584
	v_mul_f32_e32 v12, v144, v11
	v_mul_f32_e32 v13, v145, v11
	v_mul_f32_e32 v14, v146, v11
	v_mul_f32_e32 v15, v147, v11
	v_mul_f32_e32 v12, v12, v80
	v_mul_f32_e32 v13, v13, v81
	v_mul_f32_e32 v14, v14, v82
	v_mul_f32_e32 v15, v15, v83
	v_add_f32_e32 v16, 1.0, v200
	v_add_f32_e32 v17, 1.0, v201
	v_add_f32_e32 v18, 1.0, v202
	v_add_f32_e32 v19, 1.0, v203
	v_fma_f32 v12, v12, v16, v168
	v_fma_f32 v13, v13, v17, v169
	v_fma_f32 v14, v14, v18, v170
	v_fma_f32 v15, v15, v19, v171
	v_cvt_pk_bf16_f32 v20, v12, v13
	v_cvt_pk_bf16_f32 v21, v14, v15
	global_store_dwordx2 v3, v[20:21], s[26:27] offset:0
	v_mul_f32_e32 v12, v148, v11
	v_mul_f32_e32 v13, v149, v11
	v_mul_f32_e32 v14, v150, v11
	v_mul_f32_e32 v15, v151, v11
	v_mul_f32_e32 v12, v12, v84
	v_mul_f32_e32 v13, v13, v85
	v_mul_f32_e32 v14, v14, v86
	v_mul_f32_e32 v15, v15, v87
	v_add_f32_e32 v16, 1.0, v204
	v_add_f32_e32 v17, 1.0, v205
	v_add_f32_e32 v18, 1.0, v206
	v_add_f32_e32 v19, 1.0, v207
	v_fma_f32 v12, v12, v16, v172
	v_fma_f32 v13, v13, v17, v173
	v_fma_f32 v14, v14, v18, v174
	v_fma_f32 v15, v15, v19, v175
	v_cvt_pk_bf16_f32 v22, v12, v13
	v_cvt_pk_bf16_f32 v23, v14, v15
	global_store_dwordx2 v3, v[22:23], s[26:27] offset:512
	v_mul_f32_e32 v12, v152, v11
	v_mul_f32_e32 v13, v153, v11
	v_mul_f32_e32 v14, v154, v11
	v_mul_f32_e32 v15, v155, v11
	v_mul_f32_e32 v12, v12, v88
	v_mul_f32_e32 v13, v13, v89
	v_mul_f32_e32 v14, v14, v90
	v_mul_f32_e32 v15, v15, v91
	v_add_f32_e32 v16, 1.0, v208
	v_add_f32_e32 v17, 1.0, v209
	v_add_f32_e32 v18, 1.0, v210
	v_add_f32_e32 v19, 1.0, v211
	v_fma_f32 v12, v12, v16, v176
	v_fma_f32 v13, v13, v17, v177
	v_fma_f32 v14, v14, v18, v178
	v_fma_f32 v15, v15, v19, v179
	v_cvt_pk_bf16_f32 v20, v12, v13
	v_cvt_pk_bf16_f32 v21, v14, v15
	global_store_dwordx2 v3, v[20:21], s[26:27] offset:1024
	v_mul_f32_e32 v12, v156, v11
	v_mul_f32_e32 v13, v157, v11
	v_mul_f32_e32 v14, v158, v11
	v_mul_f32_e32 v15, v159, v11
	v_mul_f32_e32 v12, v12, v92
	v_mul_f32_e32 v13, v13, v93
	v_mul_f32_e32 v14, v14, v94
	v_mul_f32_e32 v15, v15, v95
	v_add_f32_e32 v16, 1.0, v212
	v_add_f32_e32 v17, 1.0, v213
	v_add_f32_e32 v18, 1.0, v214
	v_add_f32_e32 v19, 1.0, v215
	v_fma_f32 v12, v12, v16, v180
	v_fma_f32 v13, v13, v17, v181
	v_fma_f32 v14, v14, v18, v182
	v_fma_f32 v15, v15, v19, v183
	v_cvt_pk_bf16_f32 v22, v12, v13
	v_cvt_pk_bf16_f32 v23, v14, v15
	global_store_dwordx2 v3, v[22:23], s[26:27] offset:1536
	v_mul_f32_e32 v12, v160, v11
	v_mul_f32_e32 v13, v161, v11
	v_mul_f32_e32 v14, v162, v11
	v_mul_f32_e32 v15, v163, v11
	v_mul_f32_e32 v12, v12, v96
	v_mul_f32_e32 v13, v13, v97
	v_mul_f32_e32 v14, v14, v98
	v_mul_f32_e32 v15, v15, v99
	v_add_f32_e32 v16, 1.0, v216
	v_add_f32_e32 v17, 1.0, v217
	v_add_f32_e32 v18, 1.0, v218
	v_add_f32_e32 v19, 1.0, v219
	v_fma_f32 v12, v12, v16, v184
	v_fma_f32 v13, v13, v17, v185
	v_fma_f32 v14, v14, v18, v186
	v_fma_f32 v15, v15, v19, v187
	v_cvt_pk_bf16_f32 v20, v12, v13
	v_cvt_pk_bf16_f32 v21, v14, v15
	global_store_dwordx2 v3, v[20:21], s[26:27] offset:2048
	v_mul_f32_e32 v12, v232, v11
	v_mul_f32_e32 v13, v233, v11
	v_mul_f32_e32 v14, v234, v11
	v_mul_f32_e32 v15, v235, v11
	v_mul_f32_e32 v12, v12, v100
	v_mul_f32_e32 v13, v13, v101
	v_mul_f32_e32 v14, v14, v102
	v_mul_f32_e32 v15, v15, v103
	v_add_f32_e32 v16, 1.0, v220
	v_add_f32_e32 v17, 1.0, v221
	v_add_f32_e32 v18, 1.0, v222
	v_add_f32_e32 v19, 1.0, v223
	v_fma_f32 v12, v12, v16, v188
	v_fma_f32 v13, v13, v17, v189
	v_fma_f32 v14, v14, v18, v190
	v_fma_f32 v15, v15, v19, v191
	v_cvt_pk_bf16_f32 v22, v12, v13
	v_cvt_pk_bf16_f32 v23, v14, v15
	global_store_dwordx2 v3, v[22:23], s[26:27] offset:2560
	v_mul_f32_e32 v12, v236, v11
	v_mul_f32_e32 v13, v237, v11
	v_mul_f32_e32 v14, v238, v11
	v_mul_f32_e32 v15, v239, v11
	v_mul_f32_e32 v12, v12, v104
	v_mul_f32_e32 v13, v13, v105
	v_mul_f32_e32 v14, v14, v106
	v_mul_f32_e32 v15, v15, v107
	v_add_f32_e32 v16, 1.0, v224
	v_add_f32_e32 v17, 1.0, v225
	v_add_f32_e32 v18, 1.0, v226
	v_add_f32_e32 v19, 1.0, v227
	v_fma_f32 v12, v12, v16, v192
	v_fma_f32 v13, v13, v17, v193
	v_fma_f32 v14, v14, v18, v194
	v_fma_f32 v15, v15, v19, v195
	v_cvt_pk_bf16_f32 v20, v12, v13
	v_cvt_pk_bf16_f32 v21, v14, v15
	global_store_dwordx2 v3, v[20:21], s[26:27] offset:3072
	v_mul_f32_e32 v12, v240, v11
	v_mul_f32_e32 v13, v241, v11
	v_mul_f32_e32 v14, v242, v11
	v_mul_f32_e32 v15, v243, v11
	v_mul_f32_e32 v12, v12, v108
	v_mul_f32_e32 v13, v13, v109
	v_mul_f32_e32 v14, v14, v110
	v_mul_f32_e32 v15, v15, v111
	v_add_f32_e32 v16, 1.0, v228
	v_add_f32_e32 v17, 1.0, v229
	v_add_f32_e32 v18, 1.0, v230
	v_add_f32_e32 v19, 1.0, v231
	v_fma_f32 v12, v12, v16, v196
	v_fma_f32 v13, v13, v17, v197
	v_fma_f32 v14, v14, v18, v198
	v_fma_f32 v15, v15, v19, v199
	v_cvt_pk_bf16_f32 v22, v12, v13
	v_cvt_pk_bf16_f32 v23, v14, v15
	global_store_dwordx2 v3, v[22:23], s[26:27] offset:3584

; DI float lo16(unsigned u) { return __uint_as_float(u << 16); }
; DI float hi16(unsigned u) { return __uint_as_float(u & 0xFFFF0000u); }
; DI int osgpr(int v) { asm volatile("" : "+s"(v)); return v; }
; DI void post_phase(const P& p, int l, unsigned char* smem, int t0, int t1, int bstart, int bstride) {
;     ...
;     for (int rt = t0 + osgpr(bstart); rt < t1; rt += bstride) {
;       for (int rr = 0; rr < 2; ++rr) {
;         const int row = rt * 16 + wave * 2 + rr;
;         const int mr = row < NLAT ? (row >> 11) : 4;
;         const float* h = l == 0 ? (row < NLAT ? p.x + (size_t)row * DM : p.ctx + (size_t)(row - NLAT) * DM) : p.out + (size_t)row * DM;
;         float* hdst = row < NLAT ? p.out + (size_t)row * DM : hc + (size_t)(row - NLAT) * DM;
;         f32x4 y[8]; float ss = 0.f;
; #pragma unroll
;         for (int i = 0; i < 8; ++i) {
;             const u32x2 w = __builtin_nontemporal_load((const u32x2*)(yo + (size_t)row * DM + i * 256 + lane * 4));
;             y[i] = (f32x4){lo16(w.x), hi16(w.x), lo16(w.y), hi16(w.y)};
;             ss += y[i][0] * y[i][0] + y[i][1] * y[i][1] + y[i][2] * y[i][2] + y[i][3] * y[i][3];
;         }
;         ss = wave_sum(ss);
;         const float rstd = rsqrtf(ss * (1.f / 2048.f) + 1e-6f);
;         const float* md = mod + (size_t)(l * 5 + mr) * 6144;
;         float ss2 = 0.f;
; #pragma unroll
;         for (int i = 0; i < 8; ++i) {
;             const int j = i * 256 + lane * 4;
;             const f32x4 hv = __builtin_nontemporal_load((const f32x4*)(h + j)), gt = *(const f32x4*)(md + 4096 + j), nw = *(const f32x4*)(p.norm_post + l * DM + j);
.Lp1_pair:
	s_add_u32 s3, s2, s10
	s_cmpk_lt_i32 s3, 0x200
	s_cbranch_scc0 .Lp1_single
	s_lshl_b32 s12, s2, 4
	s_add_u32 s12, s12, s11
	s_lshl_b32 s14, s12, 12
	s_add_u32 s14, s14, 0x6c3c000
	s_add_u32 s14, s4, s14
	s_addc_u32 s15, s5, 0
	s_lshl_b32 s16, s12, 13
	s_add_u32 s16, s6, s16
	s_addc_u32 s17, s7, 0
	s_add_u32 s18, s16, 0x2000
	s_addc_u32 s19, s17, 0
	s_lshr_b32 s20, s12, 11
	s_add_u32 s20, s20, 5
	s_mul_i32 s20, s20, 0x6000
	s_add_u32 s20, s20, 0x4804000
	s_add_u32 s20, s4, s20
	s_addc_u32 s21, s5, 0
	s_lshl_b32 s13, s3, 4
	s_add_u32 s13, s13, s11
	s_lshl_b32 s22, s13, 12
	s_add_u32 s22, s22, 0x6c3c000
	s_add_u32 s22, s4, s22
	s_addc_u32 s23, s5, 0
	s_lshl_b32 s24, s13, 13
	s_add_u32 s24, s6, s24
	s_addc_u32 s25, s7, 0
	s_add_u32 s26, s24, 0x2000
	s_addc_u32 s27, s25, 0
	s_lshr_b32 s28, s13, 11
	s_add_u32 s28, s28, 5
	s_mul_i32 s28, s28, 0x6000
	s_add_u32 s28, s28, 0x4804000
	s_add_u32 s28, s4, s28
	s_addc_u32 s29, s5, 0
	global_load_dwordx2 v[52:53], v2, s[14:15] offset:0 nt
	global_load_dwordx2 v[54:55], v2, s[14:15] offset:512 nt
	global_load_dwordx2 v[56:57], v2, s[14:15] offset:1024 nt
	global_load_dwordx2 v[58:59], v2, s[14:15] offset:1536 nt
	global_load_dwordx2 v[60:61], v2, s[14:15] offset:2048 nt
	global_load_dwordx2 v[62:63], v2, s[14:15] offset:2560 nt
	global_load_dwordx2 v[64:65], v2, s[14:15] offset:3072 nt
	global_load_dwordx2 v[66:67], v2, s[14:15] offset:3584 nt
	global_load_dwordx2 v[68:69], v17, s[14:15] offset:0 nt
	global_load_dwordx2 v[70:71], v17, s[14:15] offset:512 nt
	global_load_dwordx2 v[72:73], v17, s[14:15] offset:1024 nt
	global_load_dwordx2 v[74:75], v17, s[14:15] offset:1536 nt
	global_load_dwordx2 v[76:77], v17, s[14:15] offset:2048 nt
	global_load_dwordx2 v[78:79], v17, s[14:15] offset:2560 nt
	global_load_dwordx2 v[80:81], v17, s[14:15] offset:3072 nt
	global_load_dwordx2 v[82:83], v17, s[14:15] offset:3584 nt
	global_load_dwordx4 v[116:119], v0, s[20:21] offset:0
	global_load_dwordx4 v[120:123], v0, s[20:21] offset:1024
	global_load_dwordx4 v[124:127], v0, s[20:21] offset:2048
	global_load_dwordx4 v[128:131], v0, s[20:21] offset:3072
	global_load_dwordx4 v[132:135], v1, s[20:21] offset:0
	global_load_dwordx4 v[136:139], v1, s[20:21] offset:1024
	global_load_dwordx4 v[140:143], v1, s[20:21] offset:2048
	global_load_dwordx4 v[144:147], v1, s[20:21] offset:3072
	global_load_dwordx4 v[84:87], v0, s[16:17] offset:0 nt
	global_load_dwordx4 v[88:91], v0, s[16:17] offset:1024 nt
	global_load_dwordx4 v[92:95], v0, s[16:17] offset:2048 nt
	global_load_dwordx4 v[96:99], v0, s[16:17] offset:3072 nt
	global_load_dwordx4 v[100:103], v1, s[16:17] offset:0 nt
	global_load_dwordx4 v[104:107], v1, s[16:17] offset:1024 nt
	global_load_dwordx4 v[108:111], v1, s[16:17] offset:2048 nt
	global_load_dwordx4 v[112:115], v1, s[16:17] offset:3072 nt
	global_load_dwordx4 v[148:151], v0, s[18:19] offset:0 nt
	global_load_dwordx4 v[152:155], v0, s[18:19] offset:1024 nt
	global_load_dwordx4 v[156:159], v0, s[18:19] offset:2048 nt
	global_load_dwordx4 v[160:163], v0, s[18:19] offset:3072 nt
	global_load_dwordx4 v[164:167], v1, s[18:19] offset:0 nt
	global_load_dwordx4 v[168:171], v1, s[18:19] offset:1024 nt
	global_load_dwordx4 v[172:175], v1, s[18:19] offset:2048 nt
	global_load_dwordx4 v[176:179], v1, s[18:19] offset:3072 nt
	s_waitcnt vmcnt(24)
	global_load_dwordx2 v[180:181], v2, s[22:23] offset:0 nt
	global_load_dwordx2 v[182:183], v2, s[22:23] offset:512 nt
	global_load_dwordx2 v[184:185], v2, s[22:23] offset:1024 nt
	global_load_dwordx2 v[186:187], v2, s[22:23] offset:1536 nt
	global_load_dwordx2 v[188:189], v2, s[22:23] offset:2048 nt
	global_load_dwordx2 v[190:191], v2, s[22:23] offset:2560 nt
	global_load_dwordx2 v[192:193], v2, s[22:23] offset:3072 nt
	global_load_dwordx2 v[194:195], v2, s[22:23] offset:3584 nt
	global_load_dwordx2 v[196:197], v17, s[22:23] offset:0 nt
	global_load_dwordx2 v[198:199], v17, s[22:23] offset:512 nt
	global_load_dwordx2 v[200:201], v17, s[22:23] offset:1024 nt
	global_load_dwordx2 v[202:203], v17, s[22:23] offset:1536 nt
	global_load_dwordx2 v[204:205], v17, s[22:23] offset:2048 nt
	global_load_dwordx2 v[206:207], v17, s[22:23] offset:2560 nt
	global_load_dwordx2 v[208:209], v17, s[22:23] offset:3072 nt
	global_load_dwordx2 v[210:211], v17, s[22:23] offset:3584 nt
	global_load_dwordx4 v[216:219], v0, s[28:29] offset:0
	global_load_dwordx4 v[220:223], v0, s[28:29] offset:1024
	global_load_dwordx4 v[224:227], v0, s[28:29] offset:2048
	global_load_dwordx4 v[228:231], v0, s[28:29] offset:3072
	global_load_dwordx4 v[232:235], v1, s[28:29] offset:0
	global_load_dwordx4 v[236:239], v1, s[28:29] offset:1024
	global_load_dwordx4 v[240:243], v1, s[28:29] offset:2048
	global_load_dwordx4 v[244:247], v1, s[28:29] offset:3072
	v_lshlrev_b32_e32 v212, 16, v52
	v_and_b32_e32 v213, 0xffff0000, v52
	v_lshlrev_b32_e32 v214, 16, v53
	v_and_b32_e32 v215, 0xffff0000, v53
	v_mul_f32_e32 v9, v212, v212
	v_mul_f32_e32 v15, v213, v213
	v_fmac_f32_e32 v9, v214, v214
	v_fmac_f32_e32 v15, v215, v215
	v_lshlrev_b32_e32 v212, 16, v54
	v_and_b32_e32 v213, 0xffff0000, v54
	v_lshlrev_b32_e32 v214, 16, v55
	v_and_b32_e32 v215, 0xffff0000, v55
	v_fmac_f32_e32 v9, v212, v212
	v_fmac_f32_e32 v15, v213, v213
	v_fmac_f32_e32 v9, v214, v214
	v_fmac_f32_e32 v15, v215, v215
	v_lshlrev_b32_e32 v212, 16, v56
	v_and_b32_e32 v213, 0xffff0000, v56
	v_lshlrev_b32_e32 v214, 16, v57
	v_and_b32_e32 v215, 0xffff0000, v57
	v_fmac_f32_e32 v9, v212, v212
	v_fmac_f32_e32 v15, v213, v213
	v_fmac_f32_e32 v9, v214, v214
	v_fmac_f32_e32 v15, v215, v215
	v_lshlrev_b32_e32 v212, 16, v58
	v_and_b32_e32 v213, 0xffff0000, v58
; DI float lo16(unsigned u) { return __uint_as_float(u << 16); }
; DI float hi16(unsigned u) { return __uint_as_float(u & 0xFFFF0000u); }
; DI float wave_sum(float v) {
; #pragma unroll
;     for (int o = 32; o >= 1; o >>= 1) v += __shfl_xor(v, o);
;     return v;
; DI void post_phase(const P& p, int l, unsigned char* smem, int t0, int t1, int bstart, int bstride) {
;     ...
;         f32x4 y[8]; float ss = 0.f;
; #pragma unroll
;         for (int i = 0; i < 8; ++i) {
;             const u32x2 w = __builtin_nontemporal_load((const u32x2*)(yo + (size_t)row * DM + i * 256 + lane * 4));
;             y[i] = (f32x4){lo16(w.x), hi16(w.x), lo16(w.y), hi16(w.y)};
;             ss += y[i][0] * y[i][0] + y[i][1] * y[i][1] + y[i][2] * y[i][2] + y[i][3] * y[i][3];
;         }
;         ss = wave_sum(ss);
;         const float rstd = rsqrtf(ss * (1.f / 2048.f) + 1e-6f);
;         const float* md = mod + (size_t)(l * 5 + mr) * 6144;
;         float ss2 = 0.f;
; #pragma unroll
;         for (int i = 0; i < 8; ++i) {
;             const int j = i * 256 + lane * 4;
;             const f32x4 hv = __builtin_nontemporal_load((const f32x4*)(h + j)), gt = *(const f32x4*)(md + 4096 + j), nw = *(const f32x4*)(p.norm_post + l * DM + j);
; #pragma unroll
;             for (int e = 0; e < 4; ++e) { y[i][e] = hv[e] + gt[e] * (y[i][e] * rstd * nw[e]); ss2 += y[i][e] * y[i][e]; }
;             __builtin_nontemporal_store(y[i], (f32x4*)(hdst + j));
	v_lshlrev_b32_e32 v214, 16, v59
	v_and_b32_e32 v215, 0xffff0000, v59
	v_fmac_f32_e32 v9, v212, v212
	v_fmac_f32_e32 v15, v213, v213
	v_fmac_f32_e32 v9, v214, v214
	v_fmac_f32_e32 v15, v215, v215
	v_lshlrev_b32_e32 v212, 16, v60
	v_and_b32_e32 v213, 0xffff0000, v60
	v_lshlrev_b32_e32 v214, 16, v61
	v_and_b32_e32 v215, 0xffff0000, v61
	v_fmac_f32_e32 v9, v212, v212
	v_fmac_f32_e32 v15, v213, v213
	v_fmac_f32_e32 v9, v214, v214
	v_fmac_f32_e32 v15, v215, v215
	v_lshlrev_b32_e32 v212, 16, v62
	v_and_b32_e32 v213, 0xffff0000, v62
	v_lshlrev_b32_e32 v214, 16, v63
	v_and_b32_e32 v215, 0xffff0000, v63
	v_fmac_f32_e32 v9, v212, v212
	v_fmac_f32_e32 v15, v213, v213
	v_fmac_f32_e32 v9, v214, v214
	v_fmac_f32_e32 v15, v215, v215
	v_lshlrev_b32_e32 v212, 16, v64
	v_and_b32_e32 v213, 0xffff0000, v64
	v_lshlrev_b32_e32 v214, 16, v65
	v_and_b32_e32 v215, 0xffff0000, v65
	v_fmac_f32_e32 v9, v212, v212
	v_fmac_f32_e32 v15, v213, v213
	v_fmac_f32_e32 v9, v214, v214
	v_fmac_f32_e32 v15, v215, v215
	v_lshlrev_b32_e32 v212, 16, v66
	v_and_b32_e32 v213, 0xffff0000, v66
	v_lshlrev_b32_e32 v214, 16, v67
	v_and_b32_e32 v215, 0xffff0000, v67
	v_fmac_f32_e32 v9, v212, v212
	v_fmac_f32_e32 v15, v213, v213
	v_fmac_f32_e32 v9, v214, v214
	v_fmac_f32_e32 v15, v215, v215
	v_add_f32_e32 v9, v9, v15
	v_lshlrev_b32_e32 v212, 16, v68
	v_and_b32_e32 v213, 0xffff0000, v68
	v_lshlrev_b32_e32 v214, 16, v69
	v_and_b32_e32 v215, 0xffff0000, v69
	v_mul_f32_e32 v10, v212, v212
	v_mul_f32_e32 v16, v213, v213
	v_fmac_f32_e32 v10, v214, v214
	v_fmac_f32_e32 v16, v215, v215
	v_lshlrev_b32_e32 v212, 16, v70
	v_and_b32_e32 v213, 0xffff0000, v70
	v_lshlrev_b32_e32 v214, 16, v71
	v_and_b32_e32 v215, 0xffff0000, v71
	v_fmac_f32_e32 v10, v212, v212
	v_fmac_f32_e32 v16, v213, v213
	v_fmac_f32_e32 v10, v214, v214
	v_fmac_f32_e32 v16, v215, v215
	v_lshlrev_b32_e32 v212, 16, v72
	v_and_b32_e32 v213, 0xffff0000, v72
	v_lshlrev_b32_e32 v214, 16, v73
	v_and_b32_e32 v215, 0xffff0000, v73
	v_fmac_f32_e32 v10, v212, v212
	v_fmac_f32_e32 v16, v213, v213
	v_fmac_f32_e32 v10, v214, v214
	v_fmac_f32_e32 v16, v215, v215
	v_lshlrev_b32_e32 v212, 16, v74
	v_and_b32_e32 v213, 0xffff0000, v74
	v_lshlrev_b32_e32 v214, 16, v75
	v_and_b32_e32 v215, 0xffff0000, v75
	v_fmac_f32_e32 v10, v212, v212
	v_fmac_f32_e32 v16, v213, v213
	v_fmac_f32_e32 v10, v214, v214
	v_fmac_f32_e32 v16, v215, v215
	v_lshlrev_b32_e32 v212, 16, v76
	v_and_b32_e32 v213, 0xffff0000, v76
	v_lshlrev_b32_e32 v214, 16, v77
	v_and_b32_e32 v215, 0xffff0000, v77
	v_fmac_f32_e32 v10, v212, v212
	v_fmac_f32_e32 v16, v213, v213
	v_fmac_f32_e32 v10, v214, v214
	v_fmac_f32_e32 v16, v215, v215
	v_lshlrev_b32_e32 v212, 16, v78
	v_and_b32_e32 v213, 0xffff0000, v78
	v_lshlrev_b32_e32 v214, 16, v79
	v_and_b32_e32 v215, 0xffff0000, v79
	v_fmac_f32_e32 v10, v212, v212
	v_fmac_f32_e32 v16, v213, v213
	v_fmac_f32_e32 v10, v214, v214
	v_fmac_f32_e32 v16, v215, v215
	v_lshlrev_b32_e32 v212, 16, v80
	v_and_b32_e32 v213, 0xffff0000, v80
	v_lshlrev_b32_e32 v214, 16, v81
	v_and_b32_e32 v215, 0xffff0000, v81
	v_fmac_f32_e32 v10, v212, v212
	v_fmac_f32_e32 v16, v213, v213
	v_fmac_f32_e32 v10, v214, v214
	v_fmac_f32_e32 v16, v215, v215
	v_lshlrev_b32_e32 v212, 16, v82
	v_and_b32_e32 v213, 0xffff0000, v82
	v_lshlrev_b32_e32 v214, 16, v83
	v_and_b32_e32 v215, 0xffff0000, v83
	v_fmac_f32_e32 v10, v212, v212
	v_fmac_f32_e32 v16, v213, v213
	v_fmac_f32_e32 v10, v214, v214
	v_fmac_f32_e32 v16, v215, v215
	v_add_f32_e32 v10, v10, v16
	s_nop 1
	v_add_f32_dpp v9, v9, v9 quad_perm:[1,0,3,2] row_mask:0xf bank_mask:0xf
	v_add_f32_dpp v10, v10, v10 quad_perm:[1,0,3,2] row_mask:0xf bank_mask:0xf
	s_nop 0
	v_add_f32_dpp v9, v9, v9 quad_perm:[2,3,0,1] row_mask:0xf bank_mask:0xf
	v_add_f32_dpp v10, v10, v10 quad_perm:[2,3,0,1] row_mask:0xf bank_mask:0xf
	s_nop 0
	v_add_f32_dpp v9, v9, v9 row_half_mirror row_mask:0xf bank_mask:0xf
	v_add_f32_dpp v10, v10, v10 row_half_mirror row_mask:0xf bank_mask:0xf
	s_nop 0
	v_add_f32_dpp v9, v9, v9 row_mirror row_mask:0xf bank_mask:0xf
	v_add_f32_dpp v10, v10, v10 row_mirror row_mask:0xf bank_mask:0xf
	s_nop 0
	v_add_f32_dpp v9, v9, v9 row_bcast:15 row_mask:0xa bank_mask:0xf
	v_add_f32_dpp v10, v10, v10 row_bcast:15 row_mask:0xa bank_mask:0xf
	s_nop 0
	v_add_f32_dpp v9, v9, v9 row_bcast:31 row_mask:0xc bank_mask:0xf
	v_add_f32_dpp v10, v10, v10 row_bcast:31 row_mask:0xc bank_mask:0xf
	s_nop 0
	v_readlane_b32 s30, v9, 63
	v_readlane_b32 s31, v10, 63
	v_mov_b32_e32 v9, s30
	v_mov_b32_e32 v10, s31
	v_mov_b32_e32 v11, 0x358637bd
	v_fmamk_f32 v9, v9, 0x3a000000, v11
	v_fmamk_f32 v10, v10, 0x3a000000, v11
	v_rsq_f32_e32 v13, v9
	v_rsq_f32_e32 v14, v10
	s_nop 0
	v_lshlrev_b32_e32 v212, 16, v52
	v_and_b32_e32 v213, 0xffff0000, v52
	v_lshlrev_b32_e32 v214, 16, v53
	v_and_b32_e32 v215, 0xffff0000, v53
	v_mul_f32_e32 v212, v13, v212
	v_mul_f32_e32 v213, v13, v213
	v_mul_f32_e32 v214, v13, v214
	v_mul_f32_e32 v215, v13, v215
	v_mul_f32_e32 v212, v20, v212
	v_mul_f32_e32 v213, v21, v213
	v_mul_f32_e32 v214, v22, v214
	v_mul_f32_e32 v215, v23, v215
	s_waitcnt vmcnt(39)
	v_fma_f32 v84, v116, v212, v84
	v_fma_f32 v85, v117, v213, v85
	v_fma_f32 v86, v118, v214, v86
	v_fma_f32 v87, v119, v215, v87
	global_store_dwordx4 v0, v[84:87], s[16:17] offset:0 sc1
	v_lshlrev_b32_e32 v212, 16, v54
	v_and_b32_e32 v213, 0xffff0000, v54
	v_lshlrev_b32_e32 v214, 16, v55
	v_and_b32_e32 v215, 0xffff0000, v55
	v_mul_f32_e32 v212, v13, v212
	v_mul_f32_e32 v213, v13, v213
	v_mul_f32_e32 v214, v13, v214
	v_mul_f32_e32 v215, v13, v215
	v_mul_f32_e32 v212, v24, v212
	v_mul_f32_e32 v213, v25, v213
	v_mul_f32_e32 v214, v26, v214
	v_mul_f32_e32 v215, v27, v215
	s_waitcnt vmcnt(39)
; DI void post_phase(const P& p, int l, unsigned char* smem, int t0, int t1, int bstart, int bstride) {
;     ...
;         for (int i = 0; i < 8; ++i) {
;             const int j = i * 256 + lane * 4;
;             const f32x4 hv = __builtin_nontemporal_load((const f32x4*)(h + j)), gt = *(const f32x4*)(md + 4096 + j), nw = *(const f32x4*)(p.norm_post + l * DM + j);
; #pragma unroll
;             for (int e = 0; e < 4; ++e) { y[i][e] = hv[e] + gt[e] * (y[i][e] * rstd * nw[e]); ss2 += y[i][e] * y[i][e]; }
;             __builtin_nontemporal_store(y[i], (f32x4*)(hdst + j));
;         }
	v_fma_f32 v88, v120, v212, v88
	v_fma_f32 v89, v121, v213, v89
	v_fma_f32 v90, v122, v214, v90
	v_fma_f32 v91, v123, v215, v91
	global_store_dwordx4 v0, v[88:91], s[16:17] offset:1024 sc1
	v_lshlrev_b32_e32 v212, 16, v56
	v_and_b32_e32 v213, 0xffff0000, v56
	v_lshlrev_b32_e32 v214, 16, v57
	v_and_b32_e32 v215, 0xffff0000, v57
	v_mul_f32_e32 v212, v13, v212
	v_mul_f32_e32 v213, v13, v213
	v_mul_f32_e32 v214, v13, v214
	v_mul_f32_e32 v215, v13, v215
	v_mul_f32_e32 v212, v28, v212
	v_mul_f32_e32 v213, v29, v213
	v_mul_f32_e32 v214, v30, v214
	v_mul_f32_e32 v215, v31, v215
	s_waitcnt vmcnt(39)
	v_fma_f32 v92, v124, v212, v92
	v_fma_f32 v93, v125, v213, v93
	v_fma_f32 v94, v126, v214, v94
	v_fma_f32 v95, v127, v215, v95
	global_store_dwordx4 v0, v[92:95], s[16:17] offset:2048 sc1
	v_lshlrev_b32_e32 v212, 16, v58
	v_and_b32_e32 v213, 0xffff0000, v58
	v_lshlrev_b32_e32 v214, 16, v59
	v_and_b32_e32 v215, 0xffff0000, v59
	v_mul_f32_e32 v212, v13, v212
	v_mul_f32_e32 v213, v13, v213
	v_mul_f32_e32 v214, v13, v214
	v_mul_f32_e32 v215, v13, v215
	v_mul_f32_e32 v212, v32, v212
	v_mul_f32_e32 v213, v33, v213
	v_mul_f32_e32 v214, v34, v214
	v_mul_f32_e32 v215, v35, v215
	s_waitcnt vmcnt(39)
	v_fma_f32 v96, v128, v212, v96
	v_fma_f32 v97, v129, v213, v97
	v_fma_f32 v98, v130, v214, v98
	v_fma_f32 v99, v131, v215, v99
	global_store_dwordx4 v0, v[96:99], s[16:17] offset:3072 sc1
	v_lshlrev_b32_e32 v212, 16, v60
	v_and_b32_e32 v213, 0xffff0000, v60
	v_lshlrev_b32_e32 v214, 16, v61
	v_and_b32_e32 v215, 0xffff0000, v61
	v_mul_f32_e32 v212, v13, v212
	v_mul_f32_e32 v213, v13, v213
	v_mul_f32_e32 v214, v13, v214
	v_mul_f32_e32 v215, v13, v215
	v_mul_f32_e32 v212, v36, v212
	v_mul_f32_e32 v213, v37, v213
	v_mul_f32_e32 v214, v38, v214
	v_mul_f32_e32 v215, v39, v215
	s_waitcnt vmcnt(39)
	v_fma_f32 v100, v132, v212, v100
	v_fma_f32 v101, v133, v213, v101
	v_fma_f32 v102, v134, v214, v102
	v_fma_f32 v103, v135, v215, v103
	global_store_dwordx4 v1, v[100:103], s[16:17] offset:0 sc1
	v_lshlrev_b32_e32 v212, 16, v62
	v_and_b32_e32 v213, 0xffff0000, v62
	v_lshlrev_b32_e32 v214, 16, v63
	v_and_b32_e32 v215, 0xffff0000, v63
	v_mul_f32_e32 v212, v13, v212
	v_mul_f32_e32 v213, v13, v213
	v_mul_f32_e32 v214, v13, v214
	v_mul_f32_e32 v215, v13, v215
	v_mul_f32_e32 v212, v40, v212
	v_mul_f32_e32 v213, v41, v213
	v_mul_f32_e32 v214, v42, v214
	v_mul_f32_e32 v215, v43, v215
	s_waitcnt vmcnt(39)
	v_fma_f32 v104, v136, v212, v104
	v_fma_f32 v105, v137, v213, v105
	v_fma_f32 v106, v138, v214, v106
	v_fma_f32 v107, v139, v215, v107
	global_store_dwordx4 v1, v[104:107], s[16:17] offset:1024 sc1
	v_lshlrev_b32_e32 v212, 16, v64
	v_and_b32_e32 v213, 0xffff0000, v64
	v_lshlrev_b32_e32 v214, 16, v65
	v_and_b32_e32 v215, 0xffff0000, v65
	v_mul_f32_e32 v212, v13, v212
	v_mul_f32_e32 v213, v13, v213
	v_mul_f32_e32 v214, v13, v214
	v_mul_f32_e32 v215, v13, v215
	v_mul_f32_e32 v212, v44, v212
	v_mul_f32_e32 v213, v45, v213
	v_mul_f32_e32 v214, v46, v214
	v_mul_f32_e32 v215, v47, v215
	s_waitcnt vmcnt(39)
	v_fma_f32 v108, v140, v212, v108
	v_fma_f32 v109, v141, v213, v109
	v_fma_f32 v110, v142, v214, v110
	v_fma_f32 v111, v143, v215, v111
	global_store_dwordx4 v1, v[108:111], s[16:17] offset:2048 sc1
	v_lshlrev_b32_e32 v212, 16, v66
	v_and_b32_e32 v213, 0xffff0000, v66
	v_lshlrev_b32_e32 v214, 16, v67
	v_and_b32_e32 v215, 0xffff0000, v67
	v_mul_f32_e32 v212, v13, v212
	v_mul_f32_e32 v213, v13, v213
	v_mul_f32_e32 v214, v13, v214
	v_mul_f32_e32 v215, v13, v215
	v_mul_f32_e32 v212, v48, v212
	v_mul_f32_e32 v213, v49, v213
	v_mul_f32_e32 v214, v50, v214
	v_mul_f32_e32 v215, v51, v215
	s_waitcnt vmcnt(39)
	v_fma_f32 v112, v144, v212, v112
	v_fma_f32 v113, v145, v213, v113
	v_fma_f32 v114, v146, v214, v114
	v_fma_f32 v115, v147, v215, v115
	global_store_dwordx4 v1, v[112:115], s[16:17] offset:3072 sc1
	global_load_dwordx4 v[84:87], v0, s[24:25] offset:0 nt
	global_load_dwordx4 v[88:91], v0, s[24:25] offset:1024 nt
	global_load_dwordx4 v[92:95], v0, s[24:25] offset:2048 nt
	global_load_dwordx4 v[96:99], v0, s[24:25] offset:3072 nt
	global_load_dwordx4 v[100:103], v1, s[24:25] offset:0 nt
	global_load_dwordx4 v[104:107], v1, s[24:25] offset:1024 nt
	global_load_dwordx4 v[108:111], v1, s[24:25] offset:2048 nt
	global_load_dwordx4 v[112:115], v1, s[24:25] offset:3072 nt
	v_lshlrev_b32_e32 v212, 16, v68
	v_and_b32_e32 v213, 0xffff0000, v68
	v_lshlrev_b32_e32 v214, 16, v69
	v_and_b32_e32 v215, 0xffff0000, v69
	v_mul_f32_e32 v212, v14, v212
	v_mul_f32_e32 v213, v14, v213
	v_mul_f32_e32 v214, v14, v214
	v_mul_f32_e32 v215, v14, v215
	v_mul_f32_e32 v212, v20, v212
	v_mul_f32_e32 v213, v21, v213
	v_mul_f32_e32 v214, v22, v214
	v_mul_f32_e32 v215, v23, v215
	s_waitcnt vmcnt(47)
	v_fma_f32 v148, v116, v212, v148
	v_fma_f32 v149, v117, v213, v149
	v_fma_f32 v150, v118, v214, v150
	v_fma_f32 v151, v119, v215, v151
	global_store_dwordx4 v0, v[148:151], s[18:19] offset:0 sc1
	v_lshlrev_b32_e32 v212, 16, v70
	v_and_b32_e32 v213, 0xffff0000, v70
	v_lshlrev_b32_e32 v214, 16, v71
	v_and_b32_e32 v215, 0xffff0000, v71
	v_mul_f32_e32 v212, v14, v212
	v_mul_f32_e32 v213, v14, v213
	v_mul_f32_e32 v214, v14, v214
	v_mul_f32_e32 v215, v14, v215
	v_mul_f32_e32 v212, v24, v212
	v_mul_f32_e32 v213, v25, v213
	v_mul_f32_e32 v214, v26, v214
	v_mul_f32_e32 v215, v27, v215
	s_waitcnt vmcnt(47)
	v_fma_f32 v152, v120, v212, v152
	v_fma_f32 v153, v121, v213, v153
	v_fma_f32 v154, v122, v214, v154
	v_fma_f32 v155, v123, v215, v155
	global_store_dwordx4 v0, v[152:155], s[18:19] offset:1024 sc1
	v_lshlrev_b32_e32 v212, 16, v72
	v_and_b32_e32 v213, 0xffff0000, v72
	v_lshlrev_b32_e32 v214, 16, v73
	v_and_b32_e32 v215, 0xffff0000, v73
	v_mul_f32_e32 v212, v14, v212
	v_mul_f32_e32 v213, v14, v213
	v_mul_f32_e32 v214, v14, v214
	v_mul_f32_e32 v215, v14, v215
	v_mul_f32_e32 v212, v28, v212
	v_mul_f32_e32 v213, v29, v213
	v_mul_f32_e32 v214, v30, v214
	v_mul_f32_e32 v215, v31, v215
	s_waitcnt vmcnt(47)
; DI float lo16(unsigned u) { return __uint_as_float(u << 16); }
; DI float hi16(unsigned u) { return __uint_as_float(u & 0xFFFF0000u); }
; DI void post_phase(const P& p, int l, unsigned char* smem, int t0, int t1, int bstart, int bstride) {
;     ...
;         f32x4 y[8]; float ss = 0.f;
; #pragma unroll
;         for (int i = 0; i < 8; ++i) {
;             const u32x2 w = __builtin_nontemporal_load((const u32x2*)(yo + (size_t)row * DM + i * 256 + lane * 4));
;             y[i] = (f32x4){lo16(w.x), hi16(w.x), lo16(w.y), hi16(w.y)};
;             ss += y[i][0] * y[i][0] + y[i][1] * y[i][1] + y[i][2] * y[i][2] + y[i][3] * y[i][3];
;         }
;         ss = wave_sum(ss);
;         const float rstd = rsqrtf(ss * (1.f / 2048.f) + 1e-6f);
;         const float* md = mod + (size_t)(l * 5 + mr) * 6144;
;         float ss2 = 0.f;
; #pragma unroll
;         for (int i = 0; i < 8; ++i) {
;             const int j = i * 256 + lane * 4;
;             const f32x4 hv = __builtin_nontemporal_load((const f32x4*)(h + j)), gt = *(const f32x4*)(md + 4096 + j), nw = *(const f32x4*)(p.norm_post + l * DM + j);
; #pragma unroll
;             for (int e = 0; e < 4; ++e) { y[i][e] = hv[e] + gt[e] * (y[i][e] * rstd * nw[e]); ss2 += y[i][e] * y[i][e]; }
;             __builtin_nontemporal_store(y[i], (f32x4*)(hdst + j));
;         }
	v_fma_f32 v156, v124, v212, v156
	v_fma_f32 v157, v125, v213, v157
	v_fma_f32 v158, v126, v214, v158
	v_fma_f32 v159, v127, v215, v159
	global_store_dwordx4 v0, v[156:159], s[18:19] offset:2048 sc1
	v_lshlrev_b32_e32 v212, 16, v74
	v_and_b32_e32 v213, 0xffff0000, v74
	v_lshlrev_b32_e32 v214, 16, v75
	v_and_b32_e32 v215, 0xffff0000, v75
	v_mul_f32_e32 v212, v14, v212
	v_mul_f32_e32 v213, v14, v213
	v_mul_f32_e32 v214, v14, v214
	v_mul_f32_e32 v215, v14, v215
	v_mul_f32_e32 v212, v32, v212
	v_mul_f32_e32 v213, v33, v213
	v_mul_f32_e32 v214, v34, v214
	v_mul_f32_e32 v215, v35, v215
	s_waitcnt vmcnt(47)
	v_fma_f32 v160, v128, v212, v160
	v_fma_f32 v161, v129, v213, v161
	v_fma_f32 v162, v130, v214, v162
	v_fma_f32 v163, v131, v215, v163
	global_store_dwordx4 v0, v[160:163], s[18:19] offset:3072 sc1
	v_lshlrev_b32_e32 v212, 16, v76
	v_and_b32_e32 v213, 0xffff0000, v76
	v_lshlrev_b32_e32 v214, 16, v77
	v_and_b32_e32 v215, 0xffff0000, v77
	v_mul_f32_e32 v212, v14, v212
	v_mul_f32_e32 v213, v14, v213
	v_mul_f32_e32 v214, v14, v214
	v_mul_f32_e32 v215, v14, v215
	v_mul_f32_e32 v212, v36, v212
	v_mul_f32_e32 v213, v37, v213
	v_mul_f32_e32 v214, v38, v214
	v_mul_f32_e32 v215, v39, v215
	s_waitcnt vmcnt(47)
	v_fma_f32 v164, v132, v212, v164
	v_fma_f32 v165, v133, v213, v165
	v_fma_f32 v166, v134, v214, v166
	v_fma_f32 v167, v135, v215, v167
	global_store_dwordx4 v1, v[164:167], s[18:19] offset:0 sc1
	v_lshlrev_b32_e32 v212, 16, v78
	v_and_b32_e32 v213, 0xffff0000, v78
	v_lshlrev_b32_e32 v214, 16, v79
	v_and_b32_e32 v215, 0xffff0000, v79
	v_mul_f32_e32 v212, v14, v212
	v_mul_f32_e32 v213, v14, v213
	v_mul_f32_e32 v214, v14, v214
	v_mul_f32_e32 v215, v14, v215
	v_mul_f32_e32 v212, v40, v212
	v_mul_f32_e32 v213, v41, v213
	v_mul_f32_e32 v214, v42, v214
	v_mul_f32_e32 v215, v43, v215
	s_waitcnt vmcnt(47)
	v_fma_f32 v168, v136, v212, v168
	v_fma_f32 v169, v137, v213, v169
	v_fma_f32 v170, v138, v214, v170
	v_fma_f32 v171, v139, v215, v171
	global_store_dwordx4 v1, v[168:171], s[18:19] offset:1024 sc1
	v_lshlrev_b32_e32 v212, 16, v80
	v_and_b32_e32 v213, 0xffff0000, v80
	v_lshlrev_b32_e32 v214, 16, v81
	v_and_b32_e32 v215, 0xffff0000, v81
	v_mul_f32_e32 v212, v14, v212
	v_mul_f32_e32 v213, v14, v213
	v_mul_f32_e32 v214, v14, v214
	v_mul_f32_e32 v215, v14, v215
	v_mul_f32_e32 v212, v44, v212
	v_mul_f32_e32 v213, v45, v213
	v_mul_f32_e32 v214, v46, v214
	v_mul_f32_e32 v215, v47, v215
	s_waitcnt vmcnt(47)
	v_fma_f32 v172, v140, v212, v172
	v_fma_f32 v173, v141, v213, v173
	v_fma_f32 v174, v142, v214, v174
	v_fma_f32 v175, v143, v215, v175
	global_store_dwordx4 v1, v[172:175], s[18:19] offset:2048 sc1
	v_lshlrev_b32_e32 v212, 16, v82
	v_and_b32_e32 v213, 0xffff0000, v82
	v_lshlrev_b32_e32 v214, 16, v83
	v_and_b32_e32 v215, 0xffff0000, v83
	v_mul_f32_e32 v212, v14, v212
	v_mul_f32_e32 v213, v14, v213
	v_mul_f32_e32 v214, v14, v214
	v_mul_f32_e32 v215, v14, v215
	v_mul_f32_e32 v212, v48, v212
	v_mul_f32_e32 v213, v49, v213
	v_mul_f32_e32 v214, v50, v214
	v_mul_f32_e32 v215, v51, v215
	s_waitcnt vmcnt(47)
	v_fma_f32 v176, v144, v212, v176
	v_fma_f32 v177, v145, v213, v177
	v_fma_f32 v178, v146, v214, v178
	v_fma_f32 v179, v147, v215, v179
	global_store_dwordx4 v1, v[176:179], s[18:19] offset:3072 sc1
	global_load_dwordx4 v[148:151], v0, s[26:27] offset:0 nt
	global_load_dwordx4 v[152:155], v0, s[26:27] offset:1024 nt
	global_load_dwordx4 v[156:159], v0, s[26:27] offset:2048 nt
	global_load_dwordx4 v[160:163], v0, s[26:27] offset:3072 nt
	global_load_dwordx4 v[164:167], v1, s[26:27] offset:0 nt
	global_load_dwordx4 v[168:171], v1, s[26:27] offset:1024 nt
	global_load_dwordx4 v[172:175], v1, s[26:27] offset:2048 nt
	global_load_dwordx4 v[176:179], v1, s[26:27] offset:3072 nt
	s_waitcnt vmcnt(40)
	v_lshlrev_b32_e32 v212, 16, v180
	v_and_b32_e32 v213, 0xffff0000, v180
	v_lshlrev_b32_e32 v214, 16, v181
	v_and_b32_e32 v215, 0xffff0000, v181
	v_mul_f32_e32 v9, v212, v212
	v_mul_f32_e32 v15, v213, v213
	v_fmac_f32_e32 v9, v214, v214
	v_fmac_f32_e32 v15, v215, v215
	v_lshlrev_b32_e32 v212, 16, v182
	v_and_b32_e32 v213, 0xffff0000, v182
	v_lshlrev_b32_e32 v214, 16, v183
	v_and_b32_e32 v215, 0xffff0000, v183
	v_fmac_f32_e32 v9, v212, v212
	v_fmac_f32_e32 v15, v213, v213
	v_fmac_f32_e32 v9, v214, v214
	v_fmac_f32_e32 v15, v215, v215
	v_lshlrev_b32_e32 v212, 16, v184
	v_and_b32_e32 v213, 0xffff0000, v184
	v_lshlrev_b32_e32 v214, 16, v185
	v_and_b32_e32 v215, 0xffff0000, v185
	v_fmac_f32_e32 v9, v212, v212
	v_fmac_f32_e32 v15, v213, v213
	v_fmac_f32_e32 v9, v214, v214
	v_fmac_f32_e32 v15, v215, v215
	v_lshlrev_b32_e32 v212, 16, v186
	v_and_b32_e32 v213, 0xffff0000, v186
	v_lshlrev_b32_e32 v214, 16, v187
	v_and_b32_e32 v215, 0xffff0000, v187
	v_fmac_f32_e32 v9, v212, v212
	v_fmac_f32_e32 v15, v213, v213
	v_fmac_f32_e32 v9, v214, v214
	v_fmac_f32_e32 v15, v215, v215
	v_lshlrev_b32_e32 v212, 16, v188
	v_and_b32_e32 v213, 0xffff0000, v188
	v_lshlrev_b32_e32 v214, 16, v189
	v_and_b32_e32 v215, 0xffff0000, v189
	v_fmac_f32_e32 v9, v212, v212
	v_fmac_f32_e32 v15, v213, v213
	v_fmac_f32_e32 v9, v214, v214
	v_fmac_f32_e32 v15, v215, v215
	v_lshlrev_b32_e32 v212, 16, v190
	v_and_b32_e32 v213, 0xffff0000, v190
	v_lshlrev_b32_e32 v214, 16, v191
	v_and_b32_e32 v215, 0xffff0000, v191
	v_fmac_f32_e32 v9, v212, v212
	v_fmac_f32_e32 v15, v213, v213
	v_fmac_f32_e32 v9, v214, v214
	v_fmac_f32_e32 v15, v215, v215
	v_lshlrev_b32_e32 v212, 16, v192
	v_and_b32_e32 v213, 0xffff0000, v192
	v_lshlrev_b32_e32 v214, 16, v193
	v_and_b32_e32 v215, 0xffff0000, v193
	v_fmac_f32_e32 v9, v212, v212
	v_fmac_f32_e32 v15, v213, v213
	v_fmac_f32_e32 v9, v214, v214
	v_fmac_f32_e32 v15, v215, v215
; DI float lo16(unsigned u) { return __uint_as_float(u << 16); }
; DI float hi16(unsigned u) { return __uint_as_float(u & 0xFFFF0000u); }
; DI float wave_sum(float v) {
; #pragma unroll
;     for (int o = 32; o >= 1; o >>= 1) v += __shfl_xor(v, o);
;     return v;
; DI void post_phase(const P& p, int l, unsigned char* smem, int t0, int t1, int bstart, int bstride) {
;     ...
;         f32x4 y[8]; float ss = 0.f;
; #pragma unroll
;         for (int i = 0; i < 8; ++i) {
;             const u32x2 w = __builtin_nontemporal_load((const u32x2*)(yo + (size_t)row * DM + i * 256 + lane * 4));
;             y[i] = (f32x4){lo16(w.x), hi16(w.x), lo16(w.y), hi16(w.y)};
;             ss += y[i][0] * y[i][0] + y[i][1] * y[i][1] + y[i][2] * y[i][2] + y[i][3] * y[i][3];
;         }
;         ss = wave_sum(ss);
;         const float rstd = rsqrtf(ss * (1.f / 2048.f) + 1e-6f);
;         const float* md = mod + (size_t)(l * 5 + mr) * 6144;
;         float ss2 = 0.f;
; #pragma unroll
;         for (int i = 0; i < 8; ++i) {
;             const int j = i * 256 + lane * 4;
;             const f32x4 hv = __builtin_nontemporal_load((const f32x4*)(h + j)), gt = *(const f32x4*)(md + 4096 + j), nw = *(const f32x4*)(p.norm_post + l * DM + j);
; #pragma unroll
;             for (int e = 0; e < 4; ++e) { y[i][e] = hv[e] + gt[e] * (y[i][e] * rstd * nw[e]); ss2 += y[i][e] * y[i][e]; }
;             __builtin_nontemporal_store(y[i], (f32x4*)(hdst + j));
	v_lshlrev_b32_e32 v212, 16, v194
	v_and_b32_e32 v213, 0xffff0000, v194
	v_lshlrev_b32_e32 v214, 16, v195
	v_and_b32_e32 v215, 0xffff0000, v195
	v_fmac_f32_e32 v9, v212, v212
	v_fmac_f32_e32 v15, v213, v213
	v_fmac_f32_e32 v9, v214, v214
	v_fmac_f32_e32 v15, v215, v215
	v_add_f32_e32 v9, v9, v15
	v_lshlrev_b32_e32 v212, 16, v196
	v_and_b32_e32 v213, 0xffff0000, v196
	v_lshlrev_b32_e32 v214, 16, v197
	v_and_b32_e32 v215, 0xffff0000, v197
	v_mul_f32_e32 v10, v212, v212
	v_mul_f32_e32 v16, v213, v213
	v_fmac_f32_e32 v10, v214, v214
	v_fmac_f32_e32 v16, v215, v215
	v_lshlrev_b32_e32 v212, 16, v198
	v_and_b32_e32 v213, 0xffff0000, v198
	v_lshlrev_b32_e32 v214, 16, v199
	v_and_b32_e32 v215, 0xffff0000, v199
	v_fmac_f32_e32 v10, v212, v212
	v_fmac_f32_e32 v16, v213, v213
	v_fmac_f32_e32 v10, v214, v214
	v_fmac_f32_e32 v16, v215, v215
	v_lshlrev_b32_e32 v212, 16, v200
	v_and_b32_e32 v213, 0xffff0000, v200
	v_lshlrev_b32_e32 v214, 16, v201
	v_and_b32_e32 v215, 0xffff0000, v201
	v_fmac_f32_e32 v10, v212, v212
	v_fmac_f32_e32 v16, v213, v213
	v_fmac_f32_e32 v10, v214, v214
	v_fmac_f32_e32 v16, v215, v215
	v_lshlrev_b32_e32 v212, 16, v202
	v_and_b32_e32 v213, 0xffff0000, v202
	v_lshlrev_b32_e32 v214, 16, v203
	v_and_b32_e32 v215, 0xffff0000, v203
	v_fmac_f32_e32 v10, v212, v212
	v_fmac_f32_e32 v16, v213, v213
	v_fmac_f32_e32 v10, v214, v214
	v_fmac_f32_e32 v16, v215, v215
	v_lshlrev_b32_e32 v212, 16, v204
	v_and_b32_e32 v213, 0xffff0000, v204
	v_lshlrev_b32_e32 v214, 16, v205
	v_and_b32_e32 v215, 0xffff0000, v205
	v_fmac_f32_e32 v10, v212, v212
	v_fmac_f32_e32 v16, v213, v213
	v_fmac_f32_e32 v10, v214, v214
	v_fmac_f32_e32 v16, v215, v215
	v_lshlrev_b32_e32 v212, 16, v206
	v_and_b32_e32 v213, 0xffff0000, v206
	v_lshlrev_b32_e32 v214, 16, v207
	v_and_b32_e32 v215, 0xffff0000, v207
	v_fmac_f32_e32 v10, v212, v212
	v_fmac_f32_e32 v16, v213, v213
	v_fmac_f32_e32 v10, v214, v214
	v_fmac_f32_e32 v16, v215, v215
	v_lshlrev_b32_e32 v212, 16, v208
	v_and_b32_e32 v213, 0xffff0000, v208
	v_lshlrev_b32_e32 v214, 16, v209
	v_and_b32_e32 v215, 0xffff0000, v209
	v_fmac_f32_e32 v10, v212, v212
	v_fmac_f32_e32 v16, v213, v213
	v_fmac_f32_e32 v10, v214, v214
	v_fmac_f32_e32 v16, v215, v215
	v_lshlrev_b32_e32 v212, 16, v210
	v_and_b32_e32 v213, 0xffff0000, v210
	v_lshlrev_b32_e32 v214, 16, v211
	v_and_b32_e32 v215, 0xffff0000, v211
	v_fmac_f32_e32 v10, v212, v212
	v_fmac_f32_e32 v16, v213, v213
	v_fmac_f32_e32 v10, v214, v214
	v_fmac_f32_e32 v16, v215, v215
	v_add_f32_e32 v10, v10, v16
	s_nop 1
	v_add_f32_dpp v9, v9, v9 quad_perm:[1,0,3,2] row_mask:0xf bank_mask:0xf
	v_add_f32_dpp v10, v10, v10 quad_perm:[1,0,3,2] row_mask:0xf bank_mask:0xf
	s_nop 0
	v_add_f32_dpp v9, v9, v9 quad_perm:[2,3,0,1] row_mask:0xf bank_mask:0xf
	v_add_f32_dpp v10, v10, v10 quad_perm:[2,3,0,1] row_mask:0xf bank_mask:0xf
	s_nop 0
	v_add_f32_dpp v9, v9, v9 row_half_mirror row_mask:0xf bank_mask:0xf
	v_add_f32_dpp v10, v10, v10 row_half_mirror row_mask:0xf bank_mask:0xf
	s_nop 0
	v_add_f32_dpp v9, v9, v9 row_mirror row_mask:0xf bank_mask:0xf
	v_add_f32_dpp v10, v10, v10 row_mirror row_mask:0xf bank_mask:0xf
	s_nop 0
	v_add_f32_dpp v9, v9, v9 row_bcast:15 row_mask:0xa bank_mask:0xf
	v_add_f32_dpp v10, v10, v10 row_bcast:15 row_mask:0xa bank_mask:0xf
	s_nop 0
	v_add_f32_dpp v9, v9, v9 row_bcast:31 row_mask:0xc bank_mask:0xf
	v_add_f32_dpp v10, v10, v10 row_bcast:31 row_mask:0xc bank_mask:0xf
	s_nop 0
	v_readlane_b32 s30, v9, 63
	v_readlane_b32 s31, v10, 63
	v_mov_b32_e32 v9, s30
	v_mov_b32_e32 v10, s31
	v_mov_b32_e32 v11, 0x358637bd
	v_fmamk_f32 v9, v9, 0x3a000000, v11
	v_fmamk_f32 v10, v10, 0x3a000000, v11
	v_rsq_f32_e32 v13, v9
	v_rsq_f32_e32 v14, v10
	s_nop 0
	v_lshlrev_b32_e32 v212, 16, v180
	v_and_b32_e32 v213, 0xffff0000, v180
	v_lshlrev_b32_e32 v214, 16, v181
	v_and_b32_e32 v215, 0xffff0000, v181
	v_mul_f32_e32 v212, v13, v212
	v_mul_f32_e32 v213, v13, v213
	v_mul_f32_e32 v214, v13, v214
	v_mul_f32_e32 v215, v13, v215
	v_mul_f32_e32 v212, v20, v212
	v_mul_f32_e32 v213, v21, v213
	v_mul_f32_e32 v214, v22, v214
	v_mul_f32_e32 v215, v23, v215
	s_waitcnt vmcnt(23)
	v_fma_f32 v84, v216, v212, v84
	v_fma_f32 v85, v217, v213, v85
	v_fma_f32 v86, v218, v214, v86
	v_fma_f32 v87, v219, v215, v87
	global_store_dwordx4 v0, v[84:87], s[24:25] offset:0 sc1
	v_lshlrev_b32_e32 v212, 16, v182
	v_and_b32_e32 v213, 0xffff0000, v182
	v_lshlrev_b32_e32 v214, 16, v183
	v_and_b32_e32 v215, 0xffff0000, v183
	v_mul_f32_e32 v212, v13, v212
	v_mul_f32_e32 v213, v13, v213
	v_mul_f32_e32 v214, v13, v214
	v_mul_f32_e32 v215, v13, v215
	v_mul_f32_e32 v212, v24, v212
	v_mul_f32_e32 v213, v25, v213
	v_mul_f32_e32 v214, v26, v214
	v_mul_f32_e32 v215, v27, v215
	s_waitcnt vmcnt(23)
	v_fma_f32 v88, v220, v212, v88
	v_fma_f32 v89, v221, v213, v89
	v_fma_f32 v90, v222, v214, v90
	v_fma_f32 v91, v223, v215, v91
	global_store_dwordx4 v0, v[88:91], s[24:25] offset:1024 sc1
	v_lshlrev_b32_e32 v212, 16, v184
	v_and_b32_e32 v213, 0xffff0000, v184
	v_lshlrev_b32_e32 v214, 16, v185
	v_and_b32_e32 v215, 0xffff0000, v185
	v_mul_f32_e32 v212, v13, v212
	v_mul_f32_e32 v213, v13, v213
	v_mul_f32_e32 v214, v13, v214
	v_mul_f32_e32 v215, v13, v215
	v_mul_f32_e32 v212, v28, v212
	v_mul_f32_e32 v213, v29, v213
	v_mul_f32_e32 v214, v30, v214
	v_mul_f32_e32 v215, v31, v215
	s_waitcnt vmcnt(23)
	v_fma_f32 v92, v224, v212, v92
	v_fma_f32 v93, v225, v213, v93
	v_fma_f32 v94, v226, v214, v94
	v_fma_f32 v95, v227, v215, v95
	global_store_dwordx4 v0, v[92:95], s[24:25] offset:2048 sc1
	v_lshlrev_b32_e32 v212, 16, v186
	v_and_b32_e32 v213, 0xffff0000, v186
	v_lshlrev_b32_e32 v214, 16, v187
	v_and_b32_e32 v215, 0xffff0000, v187
	v_mul_f32_e32 v212, v13, v212
	v_mul_f32_e32 v213, v13, v213
	v_mul_f32_e32 v214, v13, v214
	v_mul_f32_e32 v215, v13, v215
	v_mul_f32_e32 v212, v32, v212
	v_mul_f32_e32 v213, v33, v213
	v_mul_f32_e32 v214, v34, v214
	v_mul_f32_e32 v215, v35, v215
	s_waitcnt vmcnt(23)
; DI void post_phase(const P& p, int l, unsigned char* smem, int t0, int t1, int bstart, int bstride) {
;     ...
;         for (int i = 0; i < 8; ++i) {
;             const int j = i * 256 + lane * 4;
;             const f32x4 hv = __builtin_nontemporal_load((const f32x4*)(h + j)), gt = *(const f32x4*)(md + 4096 + j), nw = *(const f32x4*)(p.norm_post + l * DM + j);
; #pragma unroll
;             for (int e = 0; e < 4; ++e) { y[i][e] = hv[e] + gt[e] * (y[i][e] * rstd * nw[e]); ss2 += y[i][e] * y[i][e]; }
;             __builtin_nontemporal_store(y[i], (f32x4*)(hdst + j));
;         }
	v_fma_f32 v96, v228, v212, v96
	v_fma_f32 v97, v229, v213, v97
	v_fma_f32 v98, v230, v214, v98
	v_fma_f32 v99, v231, v215, v99
	global_store_dwordx4 v0, v[96:99], s[24:25] offset:3072 sc1
	v_lshlrev_b32_e32 v212, 16, v188
	v_and_b32_e32 v213, 0xffff0000, v188
	v_lshlrev_b32_e32 v214, 16, v189
	v_and_b32_e32 v215, 0xffff0000, v189
	v_mul_f32_e32 v212, v13, v212
	v_mul_f32_e32 v213, v13, v213
	v_mul_f32_e32 v214, v13, v214
	v_mul_f32_e32 v215, v13, v215
	v_mul_f32_e32 v212, v36, v212
	v_mul_f32_e32 v213, v37, v213
	v_mul_f32_e32 v214, v38, v214
	v_mul_f32_e32 v215, v39, v215
	s_waitcnt vmcnt(23)
	v_fma_f32 v100, v232, v212, v100
	v_fma_f32 v101, v233, v213, v101
	v_fma_f32 v102, v234, v214, v102
	v_fma_f32 v103, v235, v215, v103
	global_store_dwordx4 v1, v[100:103], s[24:25] offset:0 sc1
	v_lshlrev_b32_e32 v212, 16, v190
	v_and_b32_e32 v213, 0xffff0000, v190
	v_lshlrev_b32_e32 v214, 16, v191
	v_and_b32_e32 v215, 0xffff0000, v191
	v_mul_f32_e32 v212, v13, v212
	v_mul_f32_e32 v213, v13, v213
	v_mul_f32_e32 v214, v13, v214
	v_mul_f32_e32 v215, v13, v215
	v_mul_f32_e32 v212, v40, v212
	v_mul_f32_e32 v213, v41, v213
	v_mul_f32_e32 v214, v42, v214
	v_mul_f32_e32 v215, v43, v215
	s_waitcnt vmcnt(23)
	v_fma_f32 v104, v236, v212, v104
	v_fma_f32 v105, v237, v213, v105
	v_fma_f32 v106, v238, v214, v106
	v_fma_f32 v107, v239, v215, v107
	global_store_dwordx4 v1, v[104:107], s[24:25] offset:1024 sc1
	v_lshlrev_b32_e32 v212, 16, v192
	v_and_b32_e32 v213, 0xffff0000, v192
	v_lshlrev_b32_e32 v214, 16, v193
	v_and_b32_e32 v215, 0xffff0000, v193
	v_mul_f32_e32 v212, v13, v212
	v_mul_f32_e32 v213, v13, v213
	v_mul_f32_e32 v214, v13, v214
	v_mul_f32_e32 v215, v13, v215
	v_mul_f32_e32 v212, v44, v212
	v_mul_f32_e32 v213, v45, v213
	v_mul_f32_e32 v214, v46, v214
	v_mul_f32_e32 v215, v47, v215
	s_waitcnt vmcnt(23)
	v_fma_f32 v108, v240, v212, v108
	v_fma_f32 v109, v241, v213, v109
	v_fma_f32 v110, v242, v214, v110
	v_fma_f32 v111, v243, v215, v111
	global_store_dwordx4 v1, v[108:111], s[24:25] offset:2048 sc1
	v_lshlrev_b32_e32 v212, 16, v194
	v_and_b32_e32 v213, 0xffff0000, v194
	v_lshlrev_b32_e32 v214, 16, v195
	v_and_b32_e32 v215, 0xffff0000, v195
	v_mul_f32_e32 v212, v13, v212
	v_mul_f32_e32 v213, v13, v213
	v_mul_f32_e32 v214, v13, v214
	v_mul_f32_e32 v215, v13, v215
	v_mul_f32_e32 v212, v48, v212
	v_mul_f32_e32 v213, v49, v213
	v_mul_f32_e32 v214, v50, v214
	v_mul_f32_e32 v215, v51, v215
	s_waitcnt vmcnt(23)
	v_fma_f32 v112, v244, v212, v112
	v_fma_f32 v113, v245, v213, v113
	v_fma_f32 v114, v246, v214, v114
	v_fma_f32 v115, v247, v215, v115
	global_store_dwordx4 v1, v[112:115], s[24:25] offset:3072 sc1
	v_lshlrev_b32_e32 v212, 16, v196
	v_and_b32_e32 v213, 0xffff0000, v196
	v_lshlrev_b32_e32 v214, 16, v197
	v_and_b32_e32 v215, 0xffff0000, v197
	v_mul_f32_e32 v212, v14, v212
	v_mul_f32_e32 v213, v14, v213
	v_mul_f32_e32 v214, v14, v214
	v_mul_f32_e32 v215, v14, v215
	v_mul_f32_e32 v212, v20, v212
	v_mul_f32_e32 v213, v21, v213
	v_mul_f32_e32 v214, v22, v214
	v_mul_f32_e32 v215, v23, v215
	s_waitcnt vmcnt(15)
	v_fma_f32 v148, v216, v212, v148
	v_fma_f32 v149, v217, v213, v149
	v_fma_f32 v150, v218, v214, v150
	v_fma_f32 v151, v219, v215, v151
	global_store_dwordx4 v0, v[148:151], s[26:27] offset:0 sc1
	v_lshlrev_b32_e32 v212, 16, v198
	v_and_b32_e32 v213, 0xffff0000, v198
	v_lshlrev_b32_e32 v214, 16, v199
	v_and_b32_e32 v215, 0xffff0000, v199
	v_mul_f32_e32 v212, v14, v212
	v_mul_f32_e32 v213, v14, v213
	v_mul_f32_e32 v214, v14, v214
	v_mul_f32_e32 v215, v14, v215
	v_mul_f32_e32 v212, v24, v212
	v_mul_f32_e32 v213, v25, v213
	v_mul_f32_e32 v214, v26, v214
	v_mul_f32_e32 v215, v27, v215
	s_waitcnt vmcnt(15)
	v_fma_f32 v152, v220, v212, v152
	v_fma_f32 v153, v221, v213, v153
	v_fma_f32 v154, v222, v214, v154
	v_fma_f32 v155, v223, v215, v155
	global_store_dwordx4 v0, v[152:155], s[26:27] offset:1024 sc1
	v_lshlrev_b32_e32 v212, 16, v200
	v_and_b32_e32 v213, 0xffff0000, v200
	v_lshlrev_b32_e32 v214, 16, v201
	v_and_b32_e32 v215, 0xffff0000, v201
	v_mul_f32_e32 v212, v14, v212
	v_mul_f32_e32 v213, v14, v213
	v_mul_f32_e32 v214, v14, v214
	v_mul_f32_e32 v215, v14, v215
	v_mul_f32_e32 v212, v28, v212
	v_mul_f32_e32 v213, v29, v213
	v_mul_f32_e32 v214, v30, v214
	v_mul_f32_e32 v215, v31, v215
	s_waitcnt vmcnt(15)
	v_fma_f32 v156, v224, v212, v156
	v_fma_f32 v157, v225, v213, v157
	v_fma_f32 v158, v226, v214, v158
	v_fma_f32 v159, v227, v215, v159
	global_store_dwordx4 v0, v[156:159], s[26:27] offset:2048 sc1
	v_lshlrev_b32_e32 v212, 16, v202
	v_and_b32_e32 v213, 0xffff0000, v202
	v_lshlrev_b32_e32 v214, 16, v203
	v_and_b32_e32 v215, 0xffff0000, v203
	v_mul_f32_e32 v212, v14, v212
	v_mul_f32_e32 v213, v14, v213
	v_mul_f32_e32 v214, v14, v214
	v_mul_f32_e32 v215, v14, v215
	v_mul_f32_e32 v212, v32, v212
	v_mul_f32_e32 v213, v33, v213
	v_mul_f32_e32 v214, v34, v214
	v_mul_f32_e32 v215, v35, v215
	s_waitcnt vmcnt(15)
	v_fma_f32 v160, v228, v212, v160
	v_fma_f32 v161, v229, v213, v161
	v_fma_f32 v162, v230, v214, v162
	v_fma_f32 v163, v231, v215, v163
	global_store_dwordx4 v0, v[160:163], s[26:27] offset:3072 sc1
	v_lshlrev_b32_e32 v212, 16, v204
	v_and_b32_e32 v213, 0xffff0000, v204
	v_lshlrev_b32_e32 v214, 16, v205
	v_and_b32_e32 v215, 0xffff0000, v205
	v_mul_f32_e32 v212, v14, v212
	v_mul_f32_e32 v213, v14, v213
	v_mul_f32_e32 v214, v14, v214
	v_mul_f32_e32 v215, v14, v215
	v_mul_f32_e32 v212, v36, v212
	v_mul_f32_e32 v213, v37, v213
	v_mul_f32_e32 v214, v38, v214
	v_mul_f32_e32 v215, v39, v215
	s_waitcnt vmcnt(15)
; DI float lo16(unsigned u) { return __uint_as_float(u << 16); }
; DI float hi16(unsigned u) { return __uint_as_float(u & 0xFFFF0000u); }
; DI int osgpr(int v) { asm volatile("" : "+s"(v)); return v; }
; DI void post_phase(const P& p, int l, unsigned char* smem, int t0, int t1, int bstart, int bstride) {
;     ...
;     for (int rt = t0 + osgpr(bstart); rt < t1; rt += bstride) {
;       for (int rr = 0; rr < 2; ++rr) {
;         const int row = rt * 16 + wave * 2 + rr;
;         const int mr = row < NLAT ? (row >> 11) : 4;
;         const float* h = l == 0 ? (row < NLAT ? p.x + (size_t)row * DM : p.ctx + (size_t)(row - NLAT) * DM) : p.out + (size_t)row * DM;
;         float* hdst = row < NLAT ? p.out + (size_t)row * DM : hc + (size_t)(row - NLAT) * DM;
;         f32x4 y[8]; float ss = 0.f;
; #pragma unroll
;         for (int i = 0; i < 8; ++i) {
;             const u32x2 w = __builtin_nontemporal_load((const u32x2*)(yo + (size_t)row * DM + i * 256 + lane * 4));
;             y[i] = (f32x4){lo16(w.x), hi16(w.x), lo16(w.y), hi16(w.y)};
;             ss += y[i][0] * y[i][0] + y[i][1] * y[i][1] + y[i][2] * y[i][2] + y[i][3] * y[i][3];
;         }
;         ss = wave_sum(ss);
;         const float rstd = rsqrtf(ss * (1.f / 2048.f) + 1e-6f);
;         const float* md = mod + (size_t)(l * 5 + mr) * 6144;
;         float ss2 = 0.f;
; #pragma unroll
;         for (int i = 0; i < 8; ++i) {
;             const int j = i * 256 + lane * 4;
;             const f32x4 hv = __builtin_nontemporal_load((const f32x4*)(h + j)), gt = *(const f32x4*)(md + 4096 + j), nw = *(const f32x4*)(p.norm_post + l * DM + j);
; #pragma unroll
;             for (int e = 0; e < 4; ++e) { y[i][e] = hv[e] + gt[e] * (y[i][e] * rstd * nw[e]); ss2 += y[i][e] * y[i][e]; }
;             __builtin_nontemporal_store(y[i], (f32x4*)(hdst + j));
;         }
	v_fma_f32 v164, v232, v212, v164
	v_fma_f32 v165, v233, v213, v165
	v_fma_f32 v166, v234, v214, v166
	v_fma_f32 v167, v235, v215, v167
	global_store_dwordx4 v1, v[164:167], s[26:27] offset:0 sc1
	v_lshlrev_b32_e32 v212, 16, v206
	v_and_b32_e32 v213, 0xffff0000, v206
	v_lshlrev_b32_e32 v214, 16, v207
	v_and_b32_e32 v215, 0xffff0000, v207
	v_mul_f32_e32 v212, v14, v212
	v_mul_f32_e32 v213, v14, v213
	v_mul_f32_e32 v214, v14, v214
	v_mul_f32_e32 v215, v14, v215
	v_mul_f32_e32 v212, v40, v212
	v_mul_f32_e32 v213, v41, v213
	v_mul_f32_e32 v214, v42, v214
	v_mul_f32_e32 v215, v43, v215
	s_waitcnt vmcnt(15)
	v_fma_f32 v168, v236, v212, v168
	v_fma_f32 v169, v237, v213, v169
	v_fma_f32 v170, v238, v214, v170
	v_fma_f32 v171, v239, v215, v171
	global_store_dwordx4 v1, v[168:171], s[26:27] offset:1024 sc1
	v_lshlrev_b32_e32 v212, 16, v208
	v_and_b32_e32 v213, 0xffff0000, v208
	v_lshlrev_b32_e32 v214, 16, v209
	v_and_b32_e32 v215, 0xffff0000, v209
	v_mul_f32_e32 v212, v14, v212
	v_mul_f32_e32 v213, v14, v213
	v_mul_f32_e32 v214, v14, v214
	v_mul_f32_e32 v215, v14, v215
	v_mul_f32_e32 v212, v44, v212
	v_mul_f32_e32 v213, v45, v213
	v_mul_f32_e32 v214, v46, v214
	v_mul_f32_e32 v215, v47, v215
	s_waitcnt vmcnt(15)
	v_fma_f32 v172, v240, v212, v172
	v_fma_f32 v173, v241, v213, v173
	v_fma_f32 v174, v242, v214, v174
	v_fma_f32 v175, v243, v215, v175
	global_store_dwordx4 v1, v[172:175], s[26:27] offset:2048 sc1
	v_lshlrev_b32_e32 v212, 16, v210
	v_and_b32_e32 v213, 0xffff0000, v210
	v_lshlrev_b32_e32 v214, 16, v211
	v_and_b32_e32 v215, 0xffff0000, v211
	v_mul_f32_e32 v212, v14, v212
	v_mul_f32_e32 v213, v14, v213
	v_mul_f32_e32 v214, v14, v214
	v_mul_f32_e32 v215, v14, v215
	v_mul_f32_e32 v212, v48, v212
	v_mul_f32_e32 v213, v49, v213
	v_mul_f32_e32 v214, v50, v214
	v_mul_f32_e32 v215, v51, v215
	s_waitcnt vmcnt(15)
	v_fma_f32 v176, v244, v212, v176
	v_fma_f32 v177, v245, v213, v177
	v_fma_f32 v178, v246, v214, v178
	v_fma_f32 v179, v247, v215, v179
	global_store_dwordx4 v1, v[176:179], s[26:27] offset:3072 sc1
	s_add_u32 s2, s3, s10
	s_cmpk_lt_i32 s2, 0x200
	s_cbranch_scc1 .Lp1_pair
	s_branch .LBB0_805
.Lp1_single:
	s_lshl_b32 s12, s2, 4
	s_add_u32 s12, s12, s11
	s_lshl_b32 s14, s12, 12
	s_add_u32 s14, s14, 0x6c3c000
	s_add_u32 s14, s4, s14
	s_addc_u32 s15, s5, 0
	s_lshl_b32 s16, s12, 13
	s_add_u32 s16, s6, s16
	s_addc_u32 s17, s7, 0
	s_add_u32 s18, s16, 0x2000
	s_addc_u32 s19, s17, 0
	s_lshr_b32 s20, s12, 11
	s_add_u32 s20, s20, 5
	s_mul_i32 s20, s20, 0x6000
	s_add_u32 s20, s20, 0x4804000
	s_add_u32 s20, s4, s20
	s_addc_u32 s21, s5, 0
	global_load_dwordx2 v[52:53], v2, s[14:15] offset:0 nt
	global_load_dwordx2 v[54:55], v2, s[14:15] offset:512 nt
	global_load_dwordx2 v[56:57], v2, s[14:15] offset:1024 nt
	global_load_dwordx2 v[58:59], v2, s[14:15] offset:1536 nt
	global_load_dwordx2 v[60:61], v2, s[14:15] offset:2048 nt
	global_load_dwordx2 v[62:63], v2, s[14:15] offset:2560 nt
	global_load_dwordx2 v[64:65], v2, s[14:15] offset:3072 nt
	global_load_dwordx2 v[66:67], v2, s[14:15] offset:3584 nt
	global_load_dwordx2 v[68:69], v17, s[14:15] offset:0 nt
	global_load_dwordx2 v[70:71], v17, s[14:15] offset:512 nt
	global_load_dwordx2 v[72:73], v17, s[14:15] offset:1024 nt
	global_load_dwordx2 v[74:75], v17, s[14:15] offset:1536 nt
	global_load_dwordx2 v[76:77], v17, s[14:15] offset:2048 nt
	global_load_dwordx2 v[78:79], v17, s[14:15] offset:2560 nt
	global_load_dwordx2 v[80:81], v17, s[14:15] offset:3072 nt
	global_load_dwordx2 v[82:83], v17, s[14:15] offset:3584 nt
	global_load_dwordx4 v[116:119], v0, s[20:21] offset:0
	global_load_dwordx4 v[120:123], v0, s[20:21] offset:1024
	global_load_dwordx4 v[124:127], v0, s[20:21] offset:2048
	global_load_dwordx4 v[128:131], v0, s[20:21] offset:3072
	global_load_dwordx4 v[132:135], v1, s[20:21] offset:0
	global_load_dwordx4 v[136:139], v1, s[20:21] offset:1024
	global_load_dwordx4 v[140:143], v1, s[20:21] offset:2048
	global_load_dwordx4 v[144:147], v1, s[20:21] offset:3072
	global_load_dwordx4 v[84:87], v0, s[16:17] offset:0 nt
	global_load_dwordx4 v[88:91], v0, s[16:17] offset:1024 nt
	global_load_dwordx4 v[92:95], v0, s[16:17] offset:2048 nt
	global_load_dwordx4 v[96:99], v0, s[16:17] offset:3072 nt
	global_load_dwordx4 v[100:103], v1, s[16:17] offset:0 nt
	global_load_dwordx4 v[104:107], v1, s[16:17] offset:1024 nt
	global_load_dwordx4 v[108:111], v1, s[16:17] offset:2048 nt
	global_load_dwordx4 v[112:115], v1, s[16:17] offset:3072 nt
	global_load_dwordx4 v[148:151], v0, s[18:19] offset:0 nt
	global_load_dwordx4 v[152:155], v0, s[18:19] offset:1024 nt
	global_load_dwordx4 v[156:159], v0, s[18:19] offset:2048 nt
	global_load_dwordx4 v[160:163], v0, s[18:19] offset:3072 nt
	global_load_dwordx4 v[164:167], v1, s[18:19] offset:0 nt
	global_load_dwordx4 v[168:171], v1, s[18:19] offset:1024 nt
	global_load_dwordx4 v[172:175], v1, s[18:19] offset:2048 nt
	global_load_dwordx4 v[176:179], v1, s[18:19] offset:3072 nt
	s_waitcnt vmcnt(24)
; DI float lo16(unsigned u) { return __uint_as_float(u << 16); }
; DI float hi16(unsigned u) { return __uint_as_float(u & 0xFFFF0000u); }
; DI float wave_sum(float v) {
; #pragma unroll
;     for (int o = 32; o >= 1; o >>= 1) v += __shfl_xor(v, o);
;     return v;
; DI void post_phase(const P& p, int l, unsigned char* smem, int t0, int t1, int bstart, int bstride) {
;     ...
;         f32x4 y[8]; float ss = 0.f;
; #pragma unroll
;         for (int i = 0; i < 8; ++i) {
;             const u32x2 w = __builtin_nontemporal_load((const u32x2*)(yo + (size_t)row * DM + i * 256 + lane * 4));
;             y[i] = (f32x4){lo16(w.x), hi16(w.x), lo16(w.y), hi16(w.y)};
;             ss += y[i][0] * y[i][0] + y[i][1] * y[i][1] + y[i][2] * y[i][2] + y[i][3] * y[i][3];
;         }
;         ss = wave_sum(ss);
;         const float rstd = rsqrtf(ss * (1.f / 2048.f) + 1e-6f);
;         const float* md = mod + (size_t)(l * 5 + mr) * 6144;
;         float ss2 = 0.f;
; #pragma unroll
;         for (int i = 0; i < 8; ++i) {
;             const int j = i * 256 + lane * 4;
;             const f32x4 hv = __builtin_nontemporal_load((const f32x4*)(h + j)), gt = *(const f32x4*)(md + 4096 + j), nw = *(const f32x4*)(p.norm_post + l * DM + j);
; #pragma unroll
;             for (int e = 0; e < 4; ++e) { y[i][e] = hv[e] + gt[e] * (y[i][e] * rstd * nw[e]); ss2 += y[i][e] * y[i][e]; }
;             __builtin_nontemporal_store(y[i], (f32x4*)(hdst + j));
	v_lshlrev_b32_e32 v212, 16, v52
	v_and_b32_e32 v213, 0xffff0000, v52
	v_lshlrev_b32_e32 v214, 16, v53
	v_and_b32_e32 v215, 0xffff0000, v53
	v_mul_f32_e32 v9, v212, v212
	v_mul_f32_e32 v15, v213, v213
	v_fmac_f32_e32 v9, v214, v214
	v_fmac_f32_e32 v15, v215, v215
	v_lshlrev_b32_e32 v212, 16, v54
	v_and_b32_e32 v213, 0xffff0000, v54
	v_lshlrev_b32_e32 v214, 16, v55
	v_and_b32_e32 v215, 0xffff0000, v55
	v_fmac_f32_e32 v9, v212, v212
	v_fmac_f32_e32 v15, v213, v213
	v_fmac_f32_e32 v9, v214, v214
	v_fmac_f32_e32 v15, v215, v215
	v_lshlrev_b32_e32 v212, 16, v56
	v_and_b32_e32 v213, 0xffff0000, v56
	v_lshlrev_b32_e32 v214, 16, v57
	v_and_b32_e32 v215, 0xffff0000, v57
	v_fmac_f32_e32 v9, v212, v212
	v_fmac_f32_e32 v15, v213, v213
	v_fmac_f32_e32 v9, v214, v214
	v_fmac_f32_e32 v15, v215, v215
	v_lshlrev_b32_e32 v212, 16, v58
	v_and_b32_e32 v213, 0xffff0000, v58
	v_lshlrev_b32_e32 v214, 16, v59
	v_and_b32_e32 v215, 0xffff0000, v59
	v_fmac_f32_e32 v9, v212, v212
	v_fmac_f32_e32 v15, v213, v213
	v_fmac_f32_e32 v9, v214, v214
	v_fmac_f32_e32 v15, v215, v215
	v_lshlrev_b32_e32 v212, 16, v60
	v_and_b32_e32 v213, 0xffff0000, v60
	v_lshlrev_b32_e32 v214, 16, v61
	v_and_b32_e32 v215, 0xffff0000, v61
	v_fmac_f32_e32 v9, v212, v212
	v_fmac_f32_e32 v15, v213, v213
	v_fmac_f32_e32 v9, v214, v214
	v_fmac_f32_e32 v15, v215, v215
	v_lshlrev_b32_e32 v212, 16, v62
	v_and_b32_e32 v213, 0xffff0000, v62
	v_lshlrev_b32_e32 v214, 16, v63
	v_and_b32_e32 v215, 0xffff0000, v63
	v_fmac_f32_e32 v9, v212, v212
	v_fmac_f32_e32 v15, v213, v213
	v_fmac_f32_e32 v9, v214, v214
	v_fmac_f32_e32 v15, v215, v215
	v_lshlrev_b32_e32 v212, 16, v64
	v_and_b32_e32 v213, 0xffff0000, v64
	v_lshlrev_b32_e32 v214, 16, v65
	v_and_b32_e32 v215, 0xffff0000, v65
	v_fmac_f32_e32 v9, v212, v212
	v_fmac_f32_e32 v15, v213, v213
	v_fmac_f32_e32 v9, v214, v214
	v_fmac_f32_e32 v15, v215, v215
	v_lshlrev_b32_e32 v212, 16, v66
	v_and_b32_e32 v213, 0xffff0000, v66
	v_lshlrev_b32_e32 v214, 16, v67
	v_and_b32_e32 v215, 0xffff0000, v67
	v_fmac_f32_e32 v9, v212, v212
	v_fmac_f32_e32 v15, v213, v213
	v_fmac_f32_e32 v9, v214, v214
	v_fmac_f32_e32 v15, v215, v215
	v_add_f32_e32 v9, v9, v15
	v_lshlrev_b32_e32 v212, 16, v68
	v_and_b32_e32 v213, 0xffff0000, v68
	v_lshlrev_b32_e32 v214, 16, v69
	v_and_b32_e32 v215, 0xffff0000, v69
	v_mul_f32_e32 v10, v212, v212
	v_mul_f32_e32 v16, v213, v213
	v_fmac_f32_e32 v10, v214, v214
	v_fmac_f32_e32 v16, v215, v215
	v_lshlrev_b32_e32 v212, 16, v70
	v_and_b32_e32 v213, 0xffff0000, v70
	v_lshlrev_b32_e32 v214, 16, v71
	v_and_b32_e32 v215, 0xffff0000, v71
	v_fmac_f32_e32 v10, v212, v212
	v_fmac_f32_e32 v16, v213, v213
	v_fmac_f32_e32 v10, v214, v214
	v_fmac_f32_e32 v16, v215, v215
	v_lshlrev_b32_e32 v212, 16, v72
	v_and_b32_e32 v213, 0xffff0000, v72
	v_lshlrev_b32_e32 v214, 16, v73
	v_and_b32_e32 v215, 0xffff0000, v73
	v_fmac_f32_e32 v10, v212, v212
	v_fmac_f32_e32 v16, v213, v213
	v_fmac_f32_e32 v10, v214, v214
	v_fmac_f32_e32 v16, v215, v215
	v_lshlrev_b32_e32 v212, 16, v74
	v_and_b32_e32 v213, 0xffff0000, v74
	v_lshlrev_b32_e32 v214, 16, v75
	v_and_b32_e32 v215, 0xffff0000, v75
	v_fmac_f32_e32 v10, v212, v212
	v_fmac_f32_e32 v16, v213, v213
	v_fmac_f32_e32 v10, v214, v214
	v_fmac_f32_e32 v16, v215, v215
	v_lshlrev_b32_e32 v212, 16, v76
	v_and_b32_e32 v213, 0xffff0000, v76
	v_lshlrev_b32_e32 v214, 16, v77
	v_and_b32_e32 v215, 0xffff0000, v77
	v_fmac_f32_e32 v10, v212, v212
	v_fmac_f32_e32 v16, v213, v213
	v_fmac_f32_e32 v10, v214, v214
	v_fmac_f32_e32 v16, v215, v215
	v_lshlrev_b32_e32 v212, 16, v78
	v_and_b32_e32 v213, 0xffff0000, v78
	v_lshlrev_b32_e32 v214, 16, v79
	v_and_b32_e32 v215, 0xffff0000, v79
	v_fmac_f32_e32 v10, v212, v212
	v_fmac_f32_e32 v16, v213, v213
	v_fmac_f32_e32 v10, v214, v214
	v_fmac_f32_e32 v16, v215, v215
	v_lshlrev_b32_e32 v212, 16, v80
	v_and_b32_e32 v213, 0xffff0000, v80
	v_lshlrev_b32_e32 v214, 16, v81
	v_and_b32_e32 v215, 0xffff0000, v81
	v_fmac_f32_e32 v10, v212, v212
	v_fmac_f32_e32 v16, v213, v213
	v_fmac_f32_e32 v10, v214, v214
	v_fmac_f32_e32 v16, v215, v215
	v_lshlrev_b32_e32 v212, 16, v82
	v_and_b32_e32 v213, 0xffff0000, v82
	v_lshlrev_b32_e32 v214, 16, v83
	v_and_b32_e32 v215, 0xffff0000, v83
	v_fmac_f32_e32 v10, v212, v212
	v_fmac_f32_e32 v16, v213, v213
	v_fmac_f32_e32 v10, v214, v214
	v_fmac_f32_e32 v16, v215, v215
	v_add_f32_e32 v10, v10, v16
	s_nop 1
	v_add_f32_dpp v9, v9, v9 quad_perm:[1,0,3,2] row_mask:0xf bank_mask:0xf
	v_add_f32_dpp v10, v10, v10 quad_perm:[1,0,3,2] row_mask:0xf bank_mask:0xf
	s_nop 0
	v_add_f32_dpp v9, v9, v9 quad_perm:[2,3,0,1] row_mask:0xf bank_mask:0xf
	v_add_f32_dpp v10, v10, v10 quad_perm:[2,3,0,1] row_mask:0xf bank_mask:0xf
	s_nop 0
	v_add_f32_dpp v9, v9, v9 row_half_mirror row_mask:0xf bank_mask:0xf
	v_add_f32_dpp v10, v10, v10 row_half_mirror row_mask:0xf bank_mask:0xf
	s_nop 0
	v_add_f32_dpp v9, v9, v9 row_mirror row_mask:0xf bank_mask:0xf
	v_add_f32_dpp v10, v10, v10 row_mirror row_mask:0xf bank_mask:0xf
	s_nop 0
	v_add_f32_dpp v9, v9, v9 row_bcast:15 row_mask:0xa bank_mask:0xf
	v_add_f32_dpp v10, v10, v10 row_bcast:15 row_mask:0xa bank_mask:0xf
	s_nop 0
	v_add_f32_dpp v9, v9, v9 row_bcast:31 row_mask:0xc bank_mask:0xf
	v_add_f32_dpp v10, v10, v10 row_bcast:31 row_mask:0xc bank_mask:0xf
	s_nop 0
	v_readlane_b32 s30, v9, 63
	v_readlane_b32 s31, v10, 63
	v_mov_b32_e32 v9, s30
	v_mov_b32_e32 v10, s31
	v_mov_b32_e32 v11, 0x358637bd
	v_fmamk_f32 v9, v9, 0x3a000000, v11
	v_fmamk_f32 v10, v10, 0x3a000000, v11
	v_rsq_f32_e32 v13, v9
	v_rsq_f32_e32 v14, v10
	s_nop 0
	v_lshlrev_b32_e32 v212, 16, v52
	v_and_b32_e32 v213, 0xffff0000, v52
	v_lshlrev_b32_e32 v214, 16, v53
	v_and_b32_e32 v215, 0xffff0000, v53
	v_mul_f32_e32 v212, v13, v212
	v_mul_f32_e32 v213, v13, v213
	v_mul_f32_e32 v214, v13, v214
	v_mul_f32_e32 v215, v13, v215
	v_mul_f32_e32 v212, v20, v212
	v_mul_f32_e32 v213, v21, v213
	v_mul_f32_e32 v214, v22, v214
	v_mul_f32_e32 v215, v23, v215
	s_waitcnt vmcnt(15)
; DI void post_phase(const P& p, int l, unsigned char* smem, int t0, int t1, int bstart, int bstride) {
;     ...
;         for (int i = 0; i < 8; ++i) {
;             const int j = i * 256 + lane * 4;
;             const f32x4 hv = __builtin_nontemporal_load((const f32x4*)(h + j)), gt = *(const f32x4*)(md + 4096 + j), nw = *(const f32x4*)(p.norm_post + l * DM + j);
; #pragma unroll
;             for (int e = 0; e < 4; ++e) { y[i][e] = hv[e] + gt[e] * (y[i][e] * rstd * nw[e]); ss2 += y[i][e] * y[i][e]; }
;             __builtin_nontemporal_store(y[i], (f32x4*)(hdst + j));
;         }
	v_fma_f32 v84, v116, v212, v84
	v_fma_f32 v85, v117, v213, v85
	v_fma_f32 v86, v118, v214, v86
	v_fma_f32 v87, v119, v215, v87
	global_store_dwordx4 v0, v[84:87], s[16:17] offset:0 sc1
	v_lshlrev_b32_e32 v212, 16, v54
	v_and_b32_e32 v213, 0xffff0000, v54
	v_lshlrev_b32_e32 v214, 16, v55
	v_and_b32_e32 v215, 0xffff0000, v55
	v_mul_f32_e32 v212, v13, v212
	v_mul_f32_e32 v213, v13, v213
	v_mul_f32_e32 v214, v13, v214
	v_mul_f32_e32 v215, v13, v215
	v_mul_f32_e32 v212, v24, v212
	v_mul_f32_e32 v213, v25, v213
	v_mul_f32_e32 v214, v26, v214
	v_mul_f32_e32 v215, v27, v215
	s_waitcnt vmcnt(15)
	v_fma_f32 v88, v120, v212, v88
	v_fma_f32 v89, v121, v213, v89
	v_fma_f32 v90, v122, v214, v90
	v_fma_f32 v91, v123, v215, v91
	global_store_dwordx4 v0, v[88:91], s[16:17] offset:1024 sc1
	v_lshlrev_b32_e32 v212, 16, v56
	v_and_b32_e32 v213, 0xffff0000, v56
	v_lshlrev_b32_e32 v214, 16, v57
	v_and_b32_e32 v215, 0xffff0000, v57
	v_mul_f32_e32 v212, v13, v212
	v_mul_f32_e32 v213, v13, v213
	v_mul_f32_e32 v214, v13, v214
	v_mul_f32_e32 v215, v13, v215
	v_mul_f32_e32 v212, v28, v212
	v_mul_f32_e32 v213, v29, v213
	v_mul_f32_e32 v214, v30, v214
	v_mul_f32_e32 v215, v31, v215
	s_waitcnt vmcnt(15)
	v_fma_f32 v92, v124, v212, v92
	v_fma_f32 v93, v125, v213, v93
	v_fma_f32 v94, v126, v214, v94
	v_fma_f32 v95, v127, v215, v95
	global_store_dwordx4 v0, v[92:95], s[16:17] offset:2048 sc1
	v_lshlrev_b32_e32 v212, 16, v58
	v_and_b32_e32 v213, 0xffff0000, v58
	v_lshlrev_b32_e32 v214, 16, v59
	v_and_b32_e32 v215, 0xffff0000, v59
	v_mul_f32_e32 v212, v13, v212
	v_mul_f32_e32 v213, v13, v213
	v_mul_f32_e32 v214, v13, v214
	v_mul_f32_e32 v215, v13, v215
	v_mul_f32_e32 v212, v32, v212
	v_mul_f32_e32 v213, v33, v213
	v_mul_f32_e32 v214, v34, v214
	v_mul_f32_e32 v215, v35, v215
	s_waitcnt vmcnt(15)
	v_fma_f32 v96, v128, v212, v96
	v_fma_f32 v97, v129, v213, v97
	v_fma_f32 v98, v130, v214, v98
	v_fma_f32 v99, v131, v215, v99
	global_store_dwordx4 v0, v[96:99], s[16:17] offset:3072 sc1
	v_lshlrev_b32_e32 v212, 16, v60
	v_and_b32_e32 v213, 0xffff0000, v60
	v_lshlrev_b32_e32 v214, 16, v61
	v_and_b32_e32 v215, 0xffff0000, v61
	v_mul_f32_e32 v212, v13, v212
	v_mul_f32_e32 v213, v13, v213
	v_mul_f32_e32 v214, v13, v214
	v_mul_f32_e32 v215, v13, v215
	v_mul_f32_e32 v212, v36, v212
	v_mul_f32_e32 v213, v37, v213
	v_mul_f32_e32 v214, v38, v214
	v_mul_f32_e32 v215, v39, v215
	s_waitcnt vmcnt(15)
	v_fma_f32 v100, v132, v212, v100
	v_fma_f32 v101, v133, v213, v101
	v_fma_f32 v102, v134, v214, v102
	v_fma_f32 v103, v135, v215, v103
	global_store_dwordx4 v1, v[100:103], s[16:17] offset:0 sc1
	v_lshlrev_b32_e32 v212, 16, v62
	v_and_b32_e32 v213, 0xffff0000, v62
	v_lshlrev_b32_e32 v214, 16, v63
	v_and_b32_e32 v215, 0xffff0000, v63
	v_mul_f32_e32 v212, v13, v212
	v_mul_f32_e32 v213, v13, v213
	v_mul_f32_e32 v214, v13, v214
	v_mul_f32_e32 v215, v13, v215
	v_mul_f32_e32 v212, v40, v212
	v_mul_f32_e32 v213, v41, v213
	v_mul_f32_e32 v214, v42, v214
	v_mul_f32_e32 v215, v43, v215
	s_waitcnt vmcnt(15)
	v_fma_f32 v104, v136, v212, v104
	v_fma_f32 v105, v137, v213, v105
	v_fma_f32 v106, v138, v214, v106
	v_fma_f32 v107, v139, v215, v107
	global_store_dwordx4 v1, v[104:107], s[16:17] offset:1024 sc1
	v_lshlrev_b32_e32 v212, 16, v64
	v_and_b32_e32 v213, 0xffff0000, v64
	v_lshlrev_b32_e32 v214, 16, v65
	v_and_b32_e32 v215, 0xffff0000, v65
	v_mul_f32_e32 v212, v13, v212
	v_mul_f32_e32 v213, v13, v213
	v_mul_f32_e32 v214, v13, v214
	v_mul_f32_e32 v215, v13, v215
	v_mul_f32_e32 v212, v44, v212
	v_mul_f32_e32 v213, v45, v213
	v_mul_f32_e32 v214, v46, v214
	v_mul_f32_e32 v215, v47, v215
	s_waitcnt vmcnt(15)
	v_fma_f32 v108, v140, v212, v108
	v_fma_f32 v109, v141, v213, v109
	v_fma_f32 v110, v142, v214, v110
	v_fma_f32 v111, v143, v215, v111
	global_store_dwordx4 v1, v[108:111], s[16:17] offset:2048 sc1
	v_lshlrev_b32_e32 v212, 16, v66
	v_and_b32_e32 v213, 0xffff0000, v66
	v_lshlrev_b32_e32 v214, 16, v67
	v_and_b32_e32 v215, 0xffff0000, v67
	v_mul_f32_e32 v212, v13, v212
	v_mul_f32_e32 v213, v13, v213
	v_mul_f32_e32 v214, v13, v214
	v_mul_f32_e32 v215, v13, v215
	v_mul_f32_e32 v212, v48, v212
	v_mul_f32_e32 v213, v49, v213
	v_mul_f32_e32 v214, v50, v214
	v_mul_f32_e32 v215, v51, v215
	s_waitcnt vmcnt(15)
	v_fma_f32 v112, v144, v212, v112
	v_fma_f32 v113, v145, v213, v113
	v_fma_f32 v114, v146, v214, v114
	v_fma_f32 v115, v147, v215, v115
	global_store_dwordx4 v1, v[112:115], s[16:17] offset:3072 sc1
	v_lshlrev_b32_e32 v212, 16, v68
	v_and_b32_e32 v213, 0xffff0000, v68
	v_lshlrev_b32_e32 v214, 16, v69
	v_and_b32_e32 v215, 0xffff0000, v69
	v_mul_f32_e32 v212, v14, v212
	v_mul_f32_e32 v213, v14, v213
	v_mul_f32_e32 v214, v14, v214
	v_mul_f32_e32 v215, v14, v215
	v_mul_f32_e32 v212, v20, v212
	v_mul_f32_e32 v213, v21, v213
	v_mul_f32_e32 v214, v22, v214
	v_mul_f32_e32 v215, v23, v215
	s_waitcnt vmcnt(15)
; DI void post_phase(const P& p, int l, unsigned char* smem, int t0, int t1, int bstart, int bstride) {
;     ...
;         for (int i = 0; i < 8; ++i) {
;             const int j = i * 256 + lane * 4;
;             const f32x4 hv = __builtin_nontemporal_load((const f32x4*)(h + j)), gt = *(const f32x4*)(md + 4096 + j), nw = *(const f32x4*)(p.norm_post + l * DM + j);
; #pragma unroll
;             for (int e = 0; e < 4; ++e) { y[i][e] = hv[e] + gt[e] * (y[i][e] * rstd * nw[e]); ss2 += y[i][e] * y[i][e]; }
;             __builtin_nontemporal_store(y[i], (f32x4*)(hdst + j));
;         }
	v_fma_f32 v148, v116, v212, v148
	v_fma_f32 v149, v117, v213, v149
	v_fma_f32 v150, v118, v214, v150
	v_fma_f32 v151, v119, v215, v151
	global_store_dwordx4 v0, v[148:151], s[18:19] offset:0 sc1
	v_lshlrev_b32_e32 v212, 16, v70
	v_and_b32_e32 v213, 0xffff0000, v70
	v_lshlrev_b32_e32 v214, 16, v71
	v_and_b32_e32 v215, 0xffff0000, v71
	v_mul_f32_e32 v212, v14, v212
	v_mul_f32_e32 v213, v14, v213
	v_mul_f32_e32 v214, v14, v214
	v_mul_f32_e32 v215, v14, v215
	v_mul_f32_e32 v212, v24, v212
	v_mul_f32_e32 v213, v25, v213
	v_mul_f32_e32 v214, v26, v214
	v_mul_f32_e32 v215, v27, v215
	s_waitcnt vmcnt(15)
	v_fma_f32 v152, v120, v212, v152
	v_fma_f32 v153, v121, v213, v153
	v_fma_f32 v154, v122, v214, v154
	v_fma_f32 v155, v123, v215, v155
	global_store_dwordx4 v0, v[152:155], s[18:19] offset:1024 sc1
	v_lshlrev_b32_e32 v212, 16, v72
	v_and_b32_e32 v213, 0xffff0000, v72
	v_lshlrev_b32_e32 v214, 16, v73
	v_and_b32_e32 v215, 0xffff0000, v73
	v_mul_f32_e32 v212, v14, v212
	v_mul_f32_e32 v213, v14, v213
	v_mul_f32_e32 v214, v14, v214
	v_mul_f32_e32 v215, v14, v215
	v_mul_f32_e32 v212, v28, v212
	v_mul_f32_e32 v213, v29, v213
	v_mul_f32_e32 v214, v30, v214
	v_mul_f32_e32 v215, v31, v215
	s_waitcnt vmcnt(15)
	v_fma_f32 v156, v124, v212, v156
	v_fma_f32 v157, v125, v213, v157
	v_fma_f32 v158, v126, v214, v158
	v_fma_f32 v159, v127, v215, v159
	global_store_dwordx4 v0, v[156:159], s[18:19] offset:2048 sc1
	v_lshlrev_b32_e32 v212, 16, v74
	v_and_b32_e32 v213, 0xffff0000, v74
	v_lshlrev_b32_e32 v214, 16, v75
	v_and_b32_e32 v215, 0xffff0000, v75
	v_mul_f32_e32 v212, v14, v212
	v_mul_f32_e32 v213, v14, v213
	v_mul_f32_e32 v214, v14, v214
	v_mul_f32_e32 v215, v14, v215
	v_mul_f32_e32 v212, v32, v212
	v_mul_f32_e32 v213, v33, v213
	v_mul_f32_e32 v214, v34, v214
	v_mul_f32_e32 v215, v35, v215
	s_waitcnt vmcnt(15)
	v_fma_f32 v160, v128, v212, v160
	v_fma_f32 v161, v129, v213, v161
	v_fma_f32 v162, v130, v214, v162
	v_fma_f32 v163, v131, v215, v163
	global_store_dwordx4 v0, v[160:163], s[18:19] offset:3072 sc1
	v_lshlrev_b32_e32 v212, 16, v76
	v_and_b32_e32 v213, 0xffff0000, v76
	v_lshlrev_b32_e32 v214, 16, v77
	v_and_b32_e32 v215, 0xffff0000, v77
	v_mul_f32_e32 v212, v14, v212
	v_mul_f32_e32 v213, v14, v213
	v_mul_f32_e32 v214, v14, v214
	v_mul_f32_e32 v215, v14, v215
	v_mul_f32_e32 v212, v36, v212
	v_mul_f32_e32 v213, v37, v213
	v_mul_f32_e32 v214, v38, v214
	v_mul_f32_e32 v215, v39, v215
	s_waitcnt vmcnt(15)
	v_fma_f32 v164, v132, v212, v164
	v_fma_f32 v165, v133, v213, v165
	v_fma_f32 v166, v134, v214, v166
	v_fma_f32 v167, v135, v215, v167
	global_store_dwordx4 v1, v[164:167], s[18:19] offset:0 sc1
	v_lshlrev_b32_e32 v212, 16, v78
	v_and_b32_e32 v213, 0xffff0000, v78
	v_lshlrev_b32_e32 v214, 16, v79
	v_and_b32_e32 v215, 0xffff0000, v79
	v_mul_f32_e32 v212, v14, v212
	v_mul_f32_e32 v213, v14, v213
	v_mul_f32_e32 v214, v14, v214
	v_mul_f32_e32 v215, v14, v215
	v_mul_f32_e32 v212, v40, v212
	v_mul_f32_e32 v213, v41, v213
	v_mul_f32_e32 v214, v42, v214
	v_mul_f32_e32 v215, v43, v215
	s_waitcnt vmcnt(15)
	v_fma_f32 v168, v136, v212, v168
	v_fma_f32 v169, v137, v213, v169
	v_fma_f32 v170, v138, v214, v170
	v_fma_f32 v171, v139, v215, v171
	global_store_dwordx4 v1, v[168:171], s[18:19] offset:1024 sc1
	v_lshlrev_b32_e32 v212, 16, v80
	v_and_b32_e32 v213, 0xffff0000, v80
	v_lshlrev_b32_e32 v214, 16, v81
	v_and_b32_e32 v215, 0xffff0000, v81
	v_mul_f32_e32 v212, v14, v212
	v_mul_f32_e32 v213, v14, v213
	v_mul_f32_e32 v214, v14, v214
	v_mul_f32_e32 v215, v14, v215
	v_mul_f32_e32 v212, v44, v212
	v_mul_f32_e32 v213, v45, v213
	v_mul_f32_e32 v214, v46, v214
	v_mul_f32_e32 v215, v47, v215
	s_waitcnt vmcnt(15)
	v_fma_f32 v172, v140, v212, v172
	v_fma_f32 v173, v141, v213, v173
	v_fma_f32 v174, v142, v214, v174
	v_fma_f32 v175, v143, v215, v175
	global_store_dwordx4 v1, v[172:175], s[18:19] offset:2048 sc1
	v_lshlrev_b32_e32 v212, 16, v82
	v_and_b32_e32 v213, 0xffff0000, v82
	v_lshlrev_b32_e32 v214, 16, v83
	v_and_b32_e32 v215, 0xffff0000, v83
	v_mul_f32_e32 v212, v14, v212
	v_mul_f32_e32 v213, v14, v213
	v_mul_f32_e32 v214, v14, v214
	v_mul_f32_e32 v215, v14, v215
	v_mul_f32_e32 v212, v48, v212
	v_mul_f32_e32 v213, v49, v213
	v_mul_f32_e32 v214, v50, v214
	v_mul_f32_e32 v215, v51, v215
	s_waitcnt vmcnt(15)
	v_fma_f32 v176, v144, v212, v176
	v_fma_f32 v177, v145, v213, v177
	v_fma_f32 v178, v146, v214, v178
	v_fma_f32 v179, v147, v215, v179
	global_store_dwordx4 v1, v[176:179], s[18:19] offset:3072 sc1
	s_branch .LBB0_805

; DI float lo16(unsigned u) { return __uint_as_float(u << 16); }
; DI float hi16(unsigned u) { return __uint_as_float(u & 0xFFFF0000u); }
; DI int osgpr(int v) { asm volatile("" : "+s"(v)); return v; }
; DI void post_phase(const P& p, int l, unsigned char* smem, int t0, int t1, int bstart, int bstride) {
;     ...
;     for (int rt = t0 + osgpr(bstart); rt < t1; rt += bstride) {
;       for (int rr = 0; rr < 2; ++rr) {
;         const int row = rt * 16 + wave * 2 + rr;
;         const int mr = row < NLAT ? (row >> 11) : 4;
;         const float* h = l == 0 ? (row < NLAT ? p.x + (size_t)row * DM : p.ctx + (size_t)(row - NLAT) * DM) : p.out + (size_t)row * DM;
;         float* hdst = row < NLAT ? p.out + (size_t)row * DM : hc + (size_t)(row - NLAT) * DM;
;         f32x4 y[8]; float ss = 0.f;
; #pragma unroll
;         for (int i = 0; i < 8; ++i) {
;             const u32x2 w = __builtin_nontemporal_load((const u32x2*)(yo + (size_t)row * DM + i * 256 + lane * 4));
;             y[i] = (f32x4){lo16(w.x), hi16(w.x), lo16(w.y), hi16(w.y)};
;             ss += y[i][0] * y[i][0] + y[i][1] * y[i][1] + y[i][2] * y[i][2] + y[i][3] * y[i][3];
;         }
.Lpost0_tile:
	v_readlane_b32 s44, v254, 37
	v_readlane_b32 s45, v254, 38
	s_add_u32 s46, s0, 0x10e3c000
	s_addc_u32 s47, s1, 0
	s_lshl_b32 s28, s98, 4
	s_add_u32 s28, s28, s24
	s_lshl_b32 s36, s28, 13
	s_sub_u32 s37, s28, 0x2000
	s_lshl_b32 s37, s37, 13
	s_lshr_b32 s48, s28, 11
	s_cmpk_lt_u32 s28, 0x2000
	s_cselect_b32 s42, s92, s90
	s_cselect_b32 s43, s93, s91
	s_cselect_b32 s44, s44, s46
	s_cselect_b32 s45, s45, s47
	s_cselect_b32 s36, s36, s37
	s_cselect_b32 s48, s48, 4
	s_add_u32 s42, s42, s36
	s_addc_u32 s43, s43, 0
	s_add_u32 s44, s44, s36
	s_addc_u32 s45, s45, 0
	s_lshl_b32 s36, s28, 12
	s_add_u32 s37, s36, 0x6c3c000
	s_add_u32 s46, s0, s37
	s_addc_u32 s47, s1, 0
	s_add_u32 s37, s36, 0x483c000
	s_add_u32 s30, s0, s37
	s_addc_u32 s31, s1, 0
	s_mul_i32 s48, s48, 0x6000
	s_add_u32 s37, s48, 0x4804000
	s_add_u32 s26, s0, s37
	s_addc_u32 s27, s1, 0
	s_add_u32 s37, s48, 0x481e000
	s_add_u32 s48, s0, s37
	s_addc_u32 s49, s1, 0
	global_load_dwordx2 v[142:143], v228, s[46:47] offset:0 nt
	global_load_dwordx2 v[144:145], v228, s[46:47] offset:512 nt
	global_load_dwordx2 v[146:147], v228, s[46:47] offset:1024 nt
	global_load_dwordx2 v[148:149], v228, s[46:47] offset:1536 nt
	global_load_dwordx2 v[150:151], v228, s[46:47] offset:2048 nt
	global_load_dwordx2 v[152:153], v228, s[46:47] offset:2560 nt
	global_load_dwordx2 v[154:155], v228, s[46:47] offset:3072 nt
	global_load_dwordx2 v[156:157], v228, s[46:47] offset:3584 nt
	global_load_dwordx2 v[184:185], v229, s[46:47] offset:0 nt
	global_load_dwordx2 v[186:187], v229, s[46:47] offset:512 nt
	global_load_dwordx2 v[188:189], v229, s[46:47] offset:1024 nt
	global_load_dwordx2 v[190:191], v229, s[46:47] offset:1536 nt
	global_load_dwordx2 v[192:193], v229, s[46:47] offset:2048 nt
	global_load_dwordx2 v[194:195], v229, s[46:47] offset:2560 nt
	global_load_dwordx2 v[196:197], v229, s[46:47] offset:3072 nt
	global_load_dwordx2 v[198:199], v229, s[46:47] offset:3584 nt
	global_load_dwordx4 v[96:99], v224, s[2:3] offset:0
	global_load_dwordx4 v[100:103], v224, s[2:3] offset:1024
	global_load_dwordx4 v[104:107], v224, s[2:3] offset:2048
	global_load_dwordx4 v[108:111], v224, s[2:3] offset:3072
	global_load_dwordx4 v[112:115], v225, s[2:3] offset:0
	global_load_dwordx4 v[116:119], v225, s[2:3] offset:1024
	global_load_dwordx4 v[120:123], v225, s[2:3] offset:2048
	global_load_dwordx4 v[124:127], v225, s[2:3] offset:3072
	global_load_dwordx4 v[0:3], v224, s[42:43] offset:0 nt
	global_load_dwordx4 v[64:67], v224, s[26:27] offset:0
	global_load_dwordx4 v[4:7], v224, s[42:43] offset:1024 nt
	global_load_dwordx4 v[68:71], v224, s[26:27] offset:1024
	global_load_dwordx4 v[8:11], v224, s[42:43] offset:2048 nt
	global_load_dwordx4 v[72:75], v224, s[26:27] offset:2048
	global_load_dwordx4 v[12:15], v224, s[42:43] offset:3072 nt
	global_load_dwordx4 v[76:79], v224, s[26:27] offset:3072
	global_load_dwordx4 v[16:19], v225, s[42:43] offset:0 nt
	global_load_dwordx4 v[80:83], v225, s[26:27] offset:0
	global_load_dwordx4 v[20:23], v225, s[42:43] offset:1024 nt
	global_load_dwordx4 v[84:87], v225, s[26:27] offset:1024
	global_load_dwordx4 v[24:27], v225, s[42:43] offset:2048 nt
	global_load_dwordx4 v[88:91], v225, s[26:27] offset:2048
	global_load_dwordx4 v[28:31], v225, s[42:43] offset:3072 nt
	global_load_dwordx4 v[92:95], v225, s[26:27] offset:3072
	global_load_dwordx4 v[32:35], v226, s[42:43] offset:0 nt
	global_load_dwordx4 v[36:39], v226, s[42:43] offset:1024 nt
	global_load_dwordx4 v[40:43], v226, s[42:43] offset:2048 nt
	global_load_dwordx4 v[44:47], v226, s[42:43] offset:3072 nt
	global_load_dwordx4 v[48:51], v227, s[42:43] offset:0 nt
	global_load_dwordx4 v[52:55], v227, s[42:43] offset:1024 nt
	global_load_dwordx4 v[56:59], v227, s[42:43] offset:2048 nt
	global_load_dwordx4 v[60:63], v227, s[42:43] offset:3072 nt
	s_waitcnt vmcnt(32)
	v_lshlrev_b32_e32 v200, 16, v142
	v_and_b32_e32 v201, 0xffff0000, v142
	v_lshlrev_b32_e32 v202, 16, v143
	v_and_b32_e32 v203, 0xffff0000, v143
	v_mul_f32_e32 v236, v200, v200
	v_mul_f32_e32 v237, v201, v201
	v_fmac_f32_e32 v236, v202, v202
	v_fmac_f32_e32 v237, v203, v203
	v_lshlrev_b32_e32 v200, 16, v144
	v_and_b32_e32 v201, 0xffff0000, v144
	v_lshlrev_b32_e32 v202, 16, v145
	v_and_b32_e32 v203, 0xffff0000, v145
	v_fmac_f32_e32 v236, v200, v200
	v_fmac_f32_e32 v237, v201, v201
	v_fmac_f32_e32 v236, v202, v202
	v_fmac_f32_e32 v237, v203, v203
	v_lshlrev_b32_e32 v200, 16, v146
	v_and_b32_e32 v201, 0xffff0000, v146
	v_lshlrev_b32_e32 v202, 16, v147
	v_and_b32_e32 v203, 0xffff0000, v147
	v_fmac_f32_e32 v236, v200, v200
	v_fmac_f32_e32 v237, v201, v201
	v_fmac_f32_e32 v236, v202, v202
	v_fmac_f32_e32 v237, v203, v203
	v_lshlrev_b32_e32 v200, 16, v148
	v_and_b32_e32 v201, 0xffff0000, v148
	v_lshlrev_b32_e32 v202, 16, v149
	v_and_b32_e32 v203, 0xffff0000, v149
	v_fmac_f32_e32 v236, v200, v200
	v_fmac_f32_e32 v237, v201, v201
	v_fmac_f32_e32 v236, v202, v202
	v_fmac_f32_e32 v237, v203, v203
	v_lshlrev_b32_e32 v200, 16, v150
	v_and_b32_e32 v201, 0xffff0000, v150
	v_lshlrev_b32_e32 v202, 16, v151
	v_and_b32_e32 v203, 0xffff0000, v151
	v_fmac_f32_e32 v236, v200, v200
	v_fmac_f32_e32 v237, v201, v201
	v_fmac_f32_e32 v236, v202, v202
	v_fmac_f32_e32 v237, v203, v203
	v_lshlrev_b32_e32 v200, 16, v152
	v_and_b32_e32 v201, 0xffff0000, v152
	v_lshlrev_b32_e32 v202, 16, v153
	v_and_b32_e32 v203, 0xffff0000, v153
	v_fmac_f32_e32 v236, v200, v200
	v_fmac_f32_e32 v237, v201, v201
	v_fmac_f32_e32 v236, v202, v202
	v_fmac_f32_e32 v237, v203, v203
	v_lshlrev_b32_e32 v200, 16, v154
	v_and_b32_e32 v201, 0xffff0000, v154
	v_lshlrev_b32_e32 v202, 16, v155
	v_and_b32_e32 v203, 0xffff0000, v155
; DI void post_phase(const P& p, int l, unsigned char* smem, int t0, int t1, int bstart, int bstride) {
;     ...
;         ss = wave_sum(ss);
;         const float rstd = rsqrtf(ss * (1.f / 2048.f) + 1e-6f);
;         const float* md = mod + (size_t)(l * 5 + mr) * 6144;
;         float ss2 = 0.f;
; #pragma unroll
;         for (int i = 0; i < 8; ++i) {
;             const int j = i * 256 + lane * 4;
;             const f32x4 hv = __builtin_nontemporal_load((const f32x4*)(h + j)), gt = *(const f32x4*)(md + 4096 + j), nw = *(const f32x4*)(p.norm_post + l * DM + j);
; #pragma unroll
;             for (int e = 0; e < 4; ++e) { y[i][e] = hv[e] + gt[e] * (y[i][e] * rstd * nw[e]); ss2 += y[i][e] * y[i][e]; }
;             __builtin_nontemporal_store(y[i], (f32x4*)(hdst + j));
	v_fmac_f32_e32 v236, v200, v200
	v_fmac_f32_e32 v237, v201, v201
	v_fmac_f32_e32 v236, v202, v202
	v_fmac_f32_e32 v237, v203, v203
	v_lshlrev_b32_e32 v200, 16, v156
	v_and_b32_e32 v201, 0xffff0000, v156
	v_lshlrev_b32_e32 v202, 16, v157
	v_and_b32_e32 v203, 0xffff0000, v157
	v_fmac_f32_e32 v236, v200, v200
	v_fmac_f32_e32 v237, v201, v201
	v_fmac_f32_e32 v236, v202, v202
	v_fmac_f32_e32 v237, v203, v203
	v_add_f32_e32 v236, v236, v237
	v_lshlrev_b32_e32 v200, 16, v184
	v_and_b32_e32 v201, 0xffff0000, v184
	v_lshlrev_b32_e32 v202, 16, v185
	v_and_b32_e32 v203, 0xffff0000, v185
	v_mul_f32_e32 v238, v200, v200
	v_mul_f32_e32 v239, v201, v201
	v_fmac_f32_e32 v238, v202, v202
	v_fmac_f32_e32 v239, v203, v203
	v_lshlrev_b32_e32 v200, 16, v186
	v_and_b32_e32 v201, 0xffff0000, v186
	v_lshlrev_b32_e32 v202, 16, v187
	v_and_b32_e32 v203, 0xffff0000, v187
	v_fmac_f32_e32 v238, v200, v200
	v_fmac_f32_e32 v239, v201, v201
	v_fmac_f32_e32 v238, v202, v202
	v_fmac_f32_e32 v239, v203, v203
	v_lshlrev_b32_e32 v200, 16, v188
	v_and_b32_e32 v201, 0xffff0000, v188
	v_lshlrev_b32_e32 v202, 16, v189
	v_and_b32_e32 v203, 0xffff0000, v189
	v_fmac_f32_e32 v238, v200, v200
	v_fmac_f32_e32 v239, v201, v201
	v_fmac_f32_e32 v238, v202, v202
	v_fmac_f32_e32 v239, v203, v203
	v_lshlrev_b32_e32 v200, 16, v190
	v_and_b32_e32 v201, 0xffff0000, v190
	v_lshlrev_b32_e32 v202, 16, v191
	v_and_b32_e32 v203, 0xffff0000, v191
	v_fmac_f32_e32 v238, v200, v200
	v_fmac_f32_e32 v239, v201, v201
	v_fmac_f32_e32 v238, v202, v202
	v_fmac_f32_e32 v239, v203, v203
	v_lshlrev_b32_e32 v200, 16, v192
	v_and_b32_e32 v201, 0xffff0000, v192
	v_lshlrev_b32_e32 v202, 16, v193
	v_and_b32_e32 v203, 0xffff0000, v193
	v_fmac_f32_e32 v238, v200, v200
	v_fmac_f32_e32 v239, v201, v201
	v_fmac_f32_e32 v238, v202, v202
	v_fmac_f32_e32 v239, v203, v203
	v_lshlrev_b32_e32 v200, 16, v194
	v_and_b32_e32 v201, 0xffff0000, v194
	v_lshlrev_b32_e32 v202, 16, v195
	v_and_b32_e32 v203, 0xffff0000, v195
	v_fmac_f32_e32 v238, v200, v200
	v_fmac_f32_e32 v239, v201, v201
	v_fmac_f32_e32 v238, v202, v202
	v_fmac_f32_e32 v239, v203, v203
	v_lshlrev_b32_e32 v200, 16, v196
	v_and_b32_e32 v201, 0xffff0000, v196
	v_lshlrev_b32_e32 v202, 16, v197
	v_and_b32_e32 v203, 0xffff0000, v197
	v_fmac_f32_e32 v238, v200, v200
	v_fmac_f32_e32 v239, v201, v201
	v_fmac_f32_e32 v238, v202, v202
	v_fmac_f32_e32 v239, v203, v203
	v_lshlrev_b32_e32 v200, 16, v198
	v_and_b32_e32 v201, 0xffff0000, v198
	v_lshlrev_b32_e32 v202, 16, v199
	v_and_b32_e32 v203, 0xffff0000, v199
	v_fmac_f32_e32 v238, v200, v200
	v_fmac_f32_e32 v239, v201, v201
	v_fmac_f32_e32 v238, v202, v202
	v_fmac_f32_e32 v239, v203, v203
	v_add_f32_e32 v238, v238, v239
	s_nop 1
	v_add_f32_dpp v236, v236, v236 quad_perm:[1,0,3,2] row_mask:0xf bank_mask:0xf
	v_add_f32_dpp v238, v238, v238 quad_perm:[1,0,3,2] row_mask:0xf bank_mask:0xf
	s_nop 0
	v_add_f32_dpp v236, v236, v236 quad_perm:[2,3,0,1] row_mask:0xf bank_mask:0xf
	v_add_f32_dpp v238, v238, v238 quad_perm:[2,3,0,1] row_mask:0xf bank_mask:0xf
	s_nop 0
	v_add_f32_dpp v236, v236, v236 row_half_mirror row_mask:0xf bank_mask:0xf
	v_add_f32_dpp v238, v238, v238 row_half_mirror row_mask:0xf bank_mask:0xf
	s_nop 0
	v_add_f32_dpp v236, v236, v236 row_mirror row_mask:0xf bank_mask:0xf
	v_add_f32_dpp v238, v238, v238 row_mirror row_mask:0xf bank_mask:0xf
	s_nop 0
	v_add_f32_dpp v236, v236, v236 row_bcast:15 row_mask:0xa bank_mask:0xf
	v_add_f32_dpp v238, v238, v238 row_bcast:15 row_mask:0xa bank_mask:0xf
	s_nop 0
	v_add_f32_dpp v236, v236, v236 row_bcast:31 row_mask:0xc bank_mask:0xf
	v_add_f32_dpp v238, v238, v238 row_bcast:31 row_mask:0xc bank_mask:0xf
	s_nop 0
	v_readlane_b32 s36, v236, 63
	v_readlane_b32 s37, v238, 63
	v_mov_b32_e32 v236, s36
	v_mov_b32_e32 v238, s37
	v_mov_b32_e32 v244, 0x358637bd
	v_fmamk_f32 v236, v236, 0x3a000000, v244
	v_fmamk_f32 v238, v238, 0x3a000000, v244
	v_rsq_f32_e32 v246, v236
	v_rsq_f32_e32 v247, v238
	s_nop 0
	v_lshlrev_b32_e32 v200, 16, v142
	v_and_b32_e32 v201, 0xffff0000, v142
	v_lshlrev_b32_e32 v202, 16, v143
	v_and_b32_e32 v203, 0xffff0000, v143
	v_mul_f32_e32 v200, v246, v200
	v_mul_f32_e32 v201, v246, v201
	v_mul_f32_e32 v202, v246, v202
	v_mul_f32_e32 v203, v246, v203
	s_waitcnt vmcnt(22)
	v_mul_f32_e32 v200, v96, v200
	v_mul_f32_e32 v201, v97, v201
	v_mul_f32_e32 v202, v98, v202
	v_mul_f32_e32 v203, v99, v203
	v_fma_f32 v0, v64, v200, v0
	v_fma_f32 v1, v65, v201, v1
	v_fma_f32 v2, v66, v202, v2
	v_fma_f32 v3, v67, v203, v3
	v_mul_f32_e32 v240, v0, v0
	v_mul_f32_e32 v241, v1, v1
	v_fmac_f32_e32 v240, v2, v2
	v_fmac_f32_e32 v241, v3, v3
	global_store_dwordx4 v224, v[0:3], s[44:45] offset:0 sc1
	v_lshlrev_b32_e32 v200, 16, v144
	v_and_b32_e32 v201, 0xffff0000, v144
	v_lshlrev_b32_e32 v202, 16, v145
	v_and_b32_e32 v203, 0xffff0000, v145
	v_mul_f32_e32 v200, v246, v200
	v_mul_f32_e32 v201, v246, v201
	v_mul_f32_e32 v202, v246, v202
	v_mul_f32_e32 v203, v246, v203
	s_waitcnt vmcnt(20)
	v_mul_f32_e32 v200, v100, v200
	v_mul_f32_e32 v201, v101, v201
	v_mul_f32_e32 v202, v102, v202
	v_mul_f32_e32 v203, v103, v203
	v_fma_f32 v4, v68, v200, v4
	v_fma_f32 v5, v69, v201, v5
	v_fma_f32 v6, v70, v202, v6
	v_fma_f32 v7, v71, v203, v7
	v_fmac_f32_e32 v240, v4, v4
	v_fmac_f32_e32 v241, v5, v5
	v_fmac_f32_e32 v240, v6, v6
	v_fmac_f32_e32 v241, v7, v7
	global_store_dwordx4 v224, v[4:7], s[44:45] offset:1024 sc1
	v_lshlrev_b32_e32 v200, 16, v146
	v_and_b32_e32 v201, 0xffff0000, v146
	v_lshlrev_b32_e32 v202, 16, v147
	v_and_b32_e32 v203, 0xffff0000, v147
	v_mul_f32_e32 v200, v246, v200
	v_mul_f32_e32 v201, v246, v201
	v_mul_f32_e32 v202, v246, v202
	v_mul_f32_e32 v203, v246, v203
	s_waitcnt vmcnt(18)
; DI void post_phase(const P& p, int l, unsigned char* smem, int t0, int t1, int bstart, int bstride) {
;     ...
; #pragma unroll
;         for (int i = 0; i < 8; ++i) {
;             const int j = i * 256 + lane * 4;
;             const f32x4 hv = __builtin_nontemporal_load((const f32x4*)(h + j)), gt = *(const f32x4*)(md + 4096 + j), nw = *(const f32x4*)(p.norm_post + l * DM + j);
; #pragma unroll
;             for (int e = 0; e < 4; ++e) { y[i][e] = hv[e] + gt[e] * (y[i][e] * rstd * nw[e]); ss2 += y[i][e] * y[i][e]; }
;             __builtin_nontemporal_store(y[i], (f32x4*)(hdst + j));
;         }
	v_mul_f32_e32 v200, v104, v200
	v_mul_f32_e32 v201, v105, v201
	v_mul_f32_e32 v202, v106, v202
	v_mul_f32_e32 v203, v107, v203
	v_fma_f32 v8, v72, v200, v8
	v_fma_f32 v9, v73, v201, v9
	v_fma_f32 v10, v74, v202, v10
	v_fma_f32 v11, v75, v203, v11
	v_fmac_f32_e32 v240, v8, v8
	v_fmac_f32_e32 v241, v9, v9
	v_fmac_f32_e32 v240, v10, v10
	v_fmac_f32_e32 v241, v11, v11
	global_store_dwordx4 v224, v[8:11], s[44:45] offset:2048 sc1
	v_lshlrev_b32_e32 v200, 16, v148
	v_and_b32_e32 v201, 0xffff0000, v148
	v_lshlrev_b32_e32 v202, 16, v149
	v_and_b32_e32 v203, 0xffff0000, v149
	v_mul_f32_e32 v200, v246, v200
	v_mul_f32_e32 v201, v246, v201
	v_mul_f32_e32 v202, v246, v202
	v_mul_f32_e32 v203, v246, v203
	s_waitcnt vmcnt(16)
	v_mul_f32_e32 v200, v108, v200
	v_mul_f32_e32 v201, v109, v201
	v_mul_f32_e32 v202, v110, v202
	v_mul_f32_e32 v203, v111, v203
	v_fma_f32 v12, v76, v200, v12
	v_fma_f32 v13, v77, v201, v13
	v_fma_f32 v14, v78, v202, v14
	v_fma_f32 v15, v79, v203, v15
	v_fmac_f32_e32 v240, v12, v12
	v_fmac_f32_e32 v241, v13, v13
	v_fmac_f32_e32 v240, v14, v14
	v_fmac_f32_e32 v241, v15, v15
	global_store_dwordx4 v224, v[12:15], s[44:45] offset:3072 sc1
	v_lshlrev_b32_e32 v200, 16, v150
	v_and_b32_e32 v201, 0xffff0000, v150
	v_lshlrev_b32_e32 v202, 16, v151
	v_and_b32_e32 v203, 0xffff0000, v151
	v_mul_f32_e32 v200, v246, v200
	v_mul_f32_e32 v201, v246, v201
	v_mul_f32_e32 v202, v246, v202
	v_mul_f32_e32 v203, v246, v203
	s_waitcnt vmcnt(14)
	v_mul_f32_e32 v200, v112, v200
	v_mul_f32_e32 v201, v113, v201
	v_mul_f32_e32 v202, v114, v202
	v_mul_f32_e32 v203, v115, v203
	v_fma_f32 v16, v80, v200, v16
	v_fma_f32 v17, v81, v201, v17
	v_fma_f32 v18, v82, v202, v18
	v_fma_f32 v19, v83, v203, v19
	v_fmac_f32_e32 v240, v16, v16
	v_fmac_f32_e32 v241, v17, v17
	v_fmac_f32_e32 v240, v18, v18
	v_fmac_f32_e32 v241, v19, v19
	global_store_dwordx4 v225, v[16:19], s[44:45] offset:0 sc1
	v_lshlrev_b32_e32 v200, 16, v152
	v_and_b32_e32 v201, 0xffff0000, v152
	v_lshlrev_b32_e32 v202, 16, v153
	v_and_b32_e32 v203, 0xffff0000, v153
	v_mul_f32_e32 v200, v246, v200
	v_mul_f32_e32 v201, v246, v201
	v_mul_f32_e32 v202, v246, v202
	v_mul_f32_e32 v203, v246, v203
	s_waitcnt vmcnt(12)
	v_mul_f32_e32 v200, v116, v200
	v_mul_f32_e32 v201, v117, v201
	v_mul_f32_e32 v202, v118, v202
	v_mul_f32_e32 v203, v119, v203
	v_fma_f32 v20, v84, v200, v20
	v_fma_f32 v21, v85, v201, v21
	v_fma_f32 v22, v86, v202, v22
	v_fma_f32 v23, v87, v203, v23
	v_fmac_f32_e32 v240, v20, v20
	v_fmac_f32_e32 v241, v21, v21
	v_fmac_f32_e32 v240, v22, v22
	v_fmac_f32_e32 v241, v23, v23
	global_store_dwordx4 v225, v[20:23], s[44:45] offset:1024 sc1
	v_lshlrev_b32_e32 v200, 16, v154
	v_and_b32_e32 v201, 0xffff0000, v154
	v_lshlrev_b32_e32 v202, 16, v155
	v_and_b32_e32 v203, 0xffff0000, v155
	v_mul_f32_e32 v200, v246, v200
	v_mul_f32_e32 v201, v246, v201
	v_mul_f32_e32 v202, v246, v202
	v_mul_f32_e32 v203, v246, v203
	s_waitcnt vmcnt(10)
	v_mul_f32_e32 v200, v120, v200
	v_mul_f32_e32 v201, v121, v201
	v_mul_f32_e32 v202, v122, v202
	v_mul_f32_e32 v203, v123, v203
	v_fma_f32 v24, v88, v200, v24
	v_fma_f32 v25, v89, v201, v25
	v_fma_f32 v26, v90, v202, v26
	v_fma_f32 v27, v91, v203, v27
	v_fmac_f32_e32 v240, v24, v24
	v_fmac_f32_e32 v241, v25, v25
	v_fmac_f32_e32 v240, v26, v26
	v_fmac_f32_e32 v241, v27, v27
	global_store_dwordx4 v225, v[24:27], s[44:45] offset:2048 sc1
	v_lshlrev_b32_e32 v200, 16, v156
	v_and_b32_e32 v201, 0xffff0000, v156
	v_lshlrev_b32_e32 v202, 16, v157
	v_and_b32_e32 v203, 0xffff0000, v157
	v_mul_f32_e32 v200, v246, v200
	v_mul_f32_e32 v201, v246, v201
	v_mul_f32_e32 v202, v246, v202
	v_mul_f32_e32 v203, v246, v203
	s_waitcnt vmcnt(8)
	v_mul_f32_e32 v200, v124, v200
	v_mul_f32_e32 v201, v125, v201
	v_mul_f32_e32 v202, v126, v202
	v_mul_f32_e32 v203, v127, v203
	v_fma_f32 v28, v92, v200, v28
	v_fma_f32 v29, v93, v201, v29
	v_fma_f32 v30, v94, v202, v30
	v_fma_f32 v31, v95, v203, v31
	v_fmac_f32_e32 v240, v28, v28
	v_fmac_f32_e32 v241, v29, v29
	v_fmac_f32_e32 v240, v30, v30
	v_fmac_f32_e32 v241, v31, v31
	global_store_dwordx4 v225, v[28:31], s[44:45] offset:3072 sc1
	v_add_f32_e32 v240, v240, v241
	v_lshlrev_b32_e32 v200, 16, v184
	v_and_b32_e32 v201, 0xffff0000, v184
	v_lshlrev_b32_e32 v202, 16, v185
	v_and_b32_e32 v203, 0xffff0000, v185
	v_mul_f32_e32 v200, v247, v200
	v_mul_f32_e32 v201, v247, v201
	v_mul_f32_e32 v202, v247, v202
	v_mul_f32_e32 v203, v247, v203
	s_waitcnt vmcnt(7)
	v_mul_f32_e32 v200, v96, v200
	v_mul_f32_e32 v201, v97, v201
	v_mul_f32_e32 v202, v98, v202
	v_mul_f32_e32 v203, v99, v203
	v_fma_f32 v32, v64, v200, v32
	v_fma_f32 v33, v65, v201, v33
	v_fma_f32 v34, v66, v202, v34
	v_fma_f32 v35, v67, v203, v35
	v_mul_f32_e32 v242, v32, v32
	v_mul_f32_e32 v243, v33, v33
	v_fmac_f32_e32 v242, v34, v34
	v_fmac_f32_e32 v243, v35, v35
	global_store_dwordx4 v226, v[32:35], s[44:45] offset:0 sc1
	v_lshlrev_b32_e32 v200, 16, v186
	v_and_b32_e32 v201, 0xffff0000, v186
	v_lshlrev_b32_e32 v202, 16, v187
	v_and_b32_e32 v203, 0xffff0000, v187
	v_mul_f32_e32 v200, v247, v200
	v_mul_f32_e32 v201, v247, v201
	v_mul_f32_e32 v202, v247, v202
	v_mul_f32_e32 v203, v247, v203
	s_waitcnt vmcnt(6)
	v_mul_f32_e32 v200, v100, v200
	v_mul_f32_e32 v201, v101, v201
	v_mul_f32_e32 v202, v102, v202
	v_mul_f32_e32 v203, v103, v203
	v_fma_f32 v36, v68, v200, v36
	v_fma_f32 v37, v69, v201, v37
	v_fma_f32 v38, v70, v202, v38
	v_fma_f32 v39, v71, v203, v39
	v_fmac_f32_e32 v242, v36, v36
	v_fmac_f32_e32 v243, v37, v37
	v_fmac_f32_e32 v242, v38, v38
	v_fmac_f32_e32 v243, v39, v39
	global_store_dwordx4 v226, v[36:39], s[44:45] offset:1024 sc1
	v_lshlrev_b32_e32 v200, 16, v188
	v_and_b32_e32 v201, 0xffff0000, v188
	v_lshlrev_b32_e32 v202, 16, v189
	v_and_b32_e32 v203, 0xffff0000, v189
	v_mul_f32_e32 v200, v247, v200
	v_mul_f32_e32 v201, v247, v201
	v_mul_f32_e32 v202, v247, v202
	v_mul_f32_e32 v203, v247, v203
	s_waitcnt vmcnt(5)
; DI void post_phase(const P& p, int l, unsigned char* smem, int t0, int t1, int bstart, int bstride) {
;     ...
;         for (int i = 0; i < 8; ++i) {
;             const int j = i * 256 + lane * 4;
;             const f32x4 hv = __builtin_nontemporal_load((const f32x4*)(h + j)), gt = *(const f32x4*)(md + 4096 + j), nw = *(const f32x4*)(p.norm_post + l * DM + j);
; #pragma unroll
;             for (int e = 0; e < 4; ++e) { y[i][e] = hv[e] + gt[e] * (y[i][e] * rstd * nw[e]); ss2 += y[i][e] * y[i][e]; }
;             __builtin_nontemporal_store(y[i], (f32x4*)(hdst + j));
;         }
;         if (l == 0) {
;             ss2 = wave_sum(ss2);
;             const float rstd2 = rsqrtf(ss2 * (1.f / 2048.f) + 1e-6f);
;             const float* md1 = mod + (size_t)(5 + mr) * 6144;
; #pragma unroll
;             for (int i = 0; i < 8; ++i) {
;                 const int j = i * 256 + lane * 4;
;                 const f32x4 gw = *(const f32x4*)(p.norm_pre + DM + j), sh = *(const f32x4*)(md1 + j), scl = *(const f32x4*)(md1 + 2048 + j);
	v_mul_f32_e32 v200, v104, v200
	v_mul_f32_e32 v201, v105, v201
	v_mul_f32_e32 v202, v106, v202
	v_mul_f32_e32 v203, v107, v203
	v_fma_f32 v40, v72, v200, v40
	v_fma_f32 v41, v73, v201, v41
	v_fma_f32 v42, v74, v202, v42
	v_fma_f32 v43, v75, v203, v43
	v_fmac_f32_e32 v242, v40, v40
	v_fmac_f32_e32 v243, v41, v41
	v_fmac_f32_e32 v242, v42, v42
	v_fmac_f32_e32 v243, v43, v43
	global_store_dwordx4 v226, v[40:43], s[44:45] offset:2048 sc1
	v_lshlrev_b32_e32 v200, 16, v190
	v_and_b32_e32 v201, 0xffff0000, v190
	v_lshlrev_b32_e32 v202, 16, v191
	v_and_b32_e32 v203, 0xffff0000, v191
	v_mul_f32_e32 v200, v247, v200
	v_mul_f32_e32 v201, v247, v201
	v_mul_f32_e32 v202, v247, v202
	v_mul_f32_e32 v203, v247, v203
	s_waitcnt vmcnt(4)
	v_mul_f32_e32 v200, v108, v200
	v_mul_f32_e32 v201, v109, v201
	v_mul_f32_e32 v202, v110, v202
	v_mul_f32_e32 v203, v111, v203
	v_fma_f32 v44, v76, v200, v44
	v_fma_f32 v45, v77, v201, v45
	v_fma_f32 v46, v78, v202, v46
	v_fma_f32 v47, v79, v203, v47
	v_fmac_f32_e32 v242, v44, v44
	v_fmac_f32_e32 v243, v45, v45
	v_fmac_f32_e32 v242, v46, v46
	v_fmac_f32_e32 v243, v47, v47
	global_store_dwordx4 v226, v[44:47], s[44:45] offset:3072 sc1
	v_lshlrev_b32_e32 v200, 16, v192
	v_and_b32_e32 v201, 0xffff0000, v192
	v_lshlrev_b32_e32 v202, 16, v193
	v_and_b32_e32 v203, 0xffff0000, v193
	v_mul_f32_e32 v200, v247, v200
	v_mul_f32_e32 v201, v247, v201
	v_mul_f32_e32 v202, v247, v202
	v_mul_f32_e32 v203, v247, v203
	s_waitcnt vmcnt(3)
	v_mul_f32_e32 v200, v112, v200
	v_mul_f32_e32 v201, v113, v201
	v_mul_f32_e32 v202, v114, v202
	v_mul_f32_e32 v203, v115, v203
	v_fma_f32 v48, v80, v200, v48
	v_fma_f32 v49, v81, v201, v49
	v_fma_f32 v50, v82, v202, v50
	v_fma_f32 v51, v83, v203, v51
	v_fmac_f32_e32 v242, v48, v48
	v_fmac_f32_e32 v243, v49, v49
	v_fmac_f32_e32 v242, v50, v50
	v_fmac_f32_e32 v243, v51, v51
	global_store_dwordx4 v227, v[48:51], s[44:45] offset:0 sc1
	v_lshlrev_b32_e32 v200, 16, v194
	v_and_b32_e32 v201, 0xffff0000, v194
	v_lshlrev_b32_e32 v202, 16, v195
	v_and_b32_e32 v203, 0xffff0000, v195
	v_mul_f32_e32 v200, v247, v200
	v_mul_f32_e32 v201, v247, v201
	v_mul_f32_e32 v202, v247, v202
	v_mul_f32_e32 v203, v247, v203
	s_waitcnt vmcnt(2)
	v_mul_f32_e32 v200, v116, v200
	v_mul_f32_e32 v201, v117, v201
	v_mul_f32_e32 v202, v118, v202
	v_mul_f32_e32 v203, v119, v203
	v_fma_f32 v52, v84, v200, v52
	v_fma_f32 v53, v85, v201, v53
	v_fma_f32 v54, v86, v202, v54
	v_fma_f32 v55, v87, v203, v55
	v_fmac_f32_e32 v242, v52, v52
	v_fmac_f32_e32 v243, v53, v53
	v_fmac_f32_e32 v242, v54, v54
	v_fmac_f32_e32 v243, v55, v55
	global_store_dwordx4 v227, v[52:55], s[44:45] offset:1024 sc1
	v_lshlrev_b32_e32 v200, 16, v196
	v_and_b32_e32 v201, 0xffff0000, v196
	v_lshlrev_b32_e32 v202, 16, v197
	v_and_b32_e32 v203, 0xffff0000, v197
	v_mul_f32_e32 v200, v247, v200
	v_mul_f32_e32 v201, v247, v201
	v_mul_f32_e32 v202, v247, v202
	v_mul_f32_e32 v203, v247, v203
	s_waitcnt vmcnt(1)
	v_mul_f32_e32 v200, v120, v200
	v_mul_f32_e32 v201, v121, v201
	v_mul_f32_e32 v202, v122, v202
	v_mul_f32_e32 v203, v123, v203
	v_fma_f32 v56, v88, v200, v56
	v_fma_f32 v57, v89, v201, v57
	v_fma_f32 v58, v90, v202, v58
	v_fma_f32 v59, v91, v203, v59
	v_fmac_f32_e32 v242, v56, v56
	v_fmac_f32_e32 v243, v57, v57
	v_fmac_f32_e32 v242, v58, v58
	v_fmac_f32_e32 v243, v59, v59
	global_store_dwordx4 v227, v[56:59], s[44:45] offset:2048 sc1
	v_lshlrev_b32_e32 v200, 16, v198
	v_and_b32_e32 v201, 0xffff0000, v198
	v_lshlrev_b32_e32 v202, 16, v199
	v_and_b32_e32 v203, 0xffff0000, v199
	v_mul_f32_e32 v200, v247, v200
	v_mul_f32_e32 v201, v247, v201
	v_mul_f32_e32 v202, v247, v202
	v_mul_f32_e32 v203, v247, v203
	s_waitcnt vmcnt(0)
	v_mul_f32_e32 v200, v124, v200
	v_mul_f32_e32 v201, v125, v201
	v_mul_f32_e32 v202, v126, v202
	v_mul_f32_e32 v203, v127, v203
	v_fma_f32 v60, v92, v200, v60
	v_fma_f32 v61, v93, v201, v61
	v_fma_f32 v62, v94, v202, v62
	v_fma_f32 v63, v95, v203, v63
	v_fmac_f32_e32 v242, v60, v60
	v_fmac_f32_e32 v243, v61, v61
	v_fmac_f32_e32 v242, v62, v62
	v_fmac_f32_e32 v243, v63, v63
	global_store_dwordx4 v227, v[60:63], s[44:45] offset:3072 sc1
	v_add_f32_e32 v242, v242, v243
	global_load_dwordx4 v[64:67], v224, s[4:5] offset:0
	global_load_dwordx4 v[96:99], v224, s[48:49] offset:0
	global_load_dwordx4 v[142:145], v226, s[48:49] offset:0
	global_load_dwordx4 v[68:71], v224, s[4:5] offset:1024
	global_load_dwordx4 v[100:103], v224, s[48:49] offset:1024
	global_load_dwordx4 v[146:149], v226, s[48:49] offset:1024
	global_load_dwordx4 v[72:75], v224, s[4:5] offset:2048
	global_load_dwordx4 v[104:107], v224, s[48:49] offset:2048
	global_load_dwordx4 v[150:153], v226, s[48:49] offset:2048
	global_load_dwordx4 v[76:79], v224, s[4:5] offset:3072
	global_load_dwordx4 v[108:111], v224, s[48:49] offset:3072
	global_load_dwordx4 v[154:157], v226, s[48:49] offset:3072
	global_load_dwordx4 v[80:83], v225, s[4:5] offset:0
	global_load_dwordx4 v[112:115], v225, s[48:49] offset:0
	global_load_dwordx4 v[184:187], v227, s[48:49] offset:0
	global_load_dwordx4 v[84:87], v225, s[4:5] offset:1024
	global_load_dwordx4 v[116:119], v225, s[48:49] offset:1024
	global_load_dwordx4 v[188:191], v227, s[48:49] offset:1024
	global_load_dwordx4 v[88:91], v225, s[4:5] offset:2048
	global_load_dwordx4 v[120:123], v225, s[48:49] offset:2048
	global_load_dwordx4 v[192:195], v227, s[48:49] offset:2048
	global_load_dwordx4 v[92:95], v225, s[4:5] offset:3072
	global_load_dwordx4 v[124:127], v225, s[48:49] offset:3072
	global_load_dwordx4 v[196:199], v227, s[48:49] offset:3072
	s_nop 1
	v_add_f32_dpp v240, v240, v240 quad_perm:[1,0,3,2] row_mask:0xf bank_mask:0xf
	v_add_f32_dpp v242, v242, v242 quad_perm:[1,0,3,2] row_mask:0xf bank_mask:0xf
	s_nop 0
	v_add_f32_dpp v240, v240, v240 quad_perm:[2,3,0,1] row_mask:0xf bank_mask:0xf
	v_add_f32_dpp v242, v242, v242 quad_perm:[2,3,0,1] row_mask:0xf bank_mask:0xf
	s_nop 0
	v_add_f32_dpp v240, v240, v240 row_half_mirror row_mask:0xf bank_mask:0xf
	v_add_f32_dpp v242, v242, v242 row_half_mirror row_mask:0xf bank_mask:0xf
	s_nop 0
	v_add_f32_dpp v240, v240, v240 row_mirror row_mask:0xf bank_mask:0xf
	v_add_f32_dpp v242, v242, v242 row_mirror row_mask:0xf bank_mask:0xf
	s_nop 0
	v_add_f32_dpp v240, v240, v240 row_bcast:15 row_mask:0xa bank_mask:0xf
	v_add_f32_dpp v242, v242, v242 row_bcast:15 row_mask:0xa bank_mask:0xf
	s_nop 0
	v_add_f32_dpp v240, v240, v240 row_bcast:31 row_mask:0xc bank_mask:0xf
	v_add_f32_dpp v242, v242, v242 row_bcast:31 row_mask:0xc bank_mask:0xf
	s_nop 0
	v_readlane_b32 s36, v240, 63
	v_readlane_b32 s37, v242, 63
	v_mov_b32_e32 v240, s36
	v_mov_b32_e32 v242, s37
	v_mov_b32_e32 v244, 0x358637bd
	v_fmamk_f32 v240, v240, 0x3a000000, v244
	v_fmamk_f32 v242, v242, 0x3a000000, v244
	v_rsq_f32_e32 v246, v240
	v_rsq_f32_e32 v247, v242
	s_nop 0
	v_mul_f32_e32 v200, v0, v246
	v_mul_f32_e32 v201, v1, v246
	v_mul_f32_e32 v202, v2, v246
	v_mul_f32_e32 v203, v3, v246
	s_waitcnt vmcnt(21)
; DI void post_phase(const P& p, int l, unsigned char* smem, int t0, int t1, int bstart, int bstride) {
;     ...
;             for (int i = 0; i < 8; ++i) {
;                 const int j = i * 256 + lane * 4;
;                 const f32x4 gw = *(const f32x4*)(p.norm_pre + DM + j), sh = *(const f32x4*)(md1 + j), scl = *(const f32x4*)(md1 + 2048 + j);
;                 float o[4];
; #pragma unroll
;                 for (int e = 0; e < 4; ++e) o[e] = y[i][e] * rstd2 * gw[e] * (1.f + scl[e]) + sh[e];
;                 u32x2 w; w.x = pk2(o[0], o[1]); w.y = pk2(o[2], o[3]);
;                 *(u32x2*)(nb + (size_t)row * DM + j) = w;
;             }
	v_mul_f32_e32 v200, v200, v64
	v_mul_f32_e32 v201, v201, v65
	v_mul_f32_e32 v202, v202, v66
	v_mul_f32_e32 v203, v203, v67
	v_add_f32_e32 v204, 1.0, v142
	v_add_f32_e32 v205, 1.0, v143
	v_add_f32_e32 v206, 1.0, v144
	v_add_f32_e32 v207, 1.0, v145
	v_fma_f32 v200, v200, v204, v96
	v_fma_f32 v201, v201, v205, v97
	v_fma_f32 v202, v202, v206, v98
	v_fma_f32 v203, v203, v207, v99
	v_cvt_pk_bf16_f32 v208, v200, v201
	v_cvt_pk_bf16_f32 v209, v202, v203
	global_store_dwordx2 v228, v[208:209], s[30:31] offset:0
	v_mul_f32_e32 v200, v4, v246
	v_mul_f32_e32 v201, v5, v246
	v_mul_f32_e32 v202, v6, v246
	v_mul_f32_e32 v203, v7, v246
	s_waitcnt vmcnt(18)
	v_mul_f32_e32 v200, v200, v68
	v_mul_f32_e32 v201, v201, v69
	v_mul_f32_e32 v202, v202, v70
	v_mul_f32_e32 v203, v203, v71
	v_add_f32_e32 v204, 1.0, v146
	v_add_f32_e32 v205, 1.0, v147
	v_add_f32_e32 v206, 1.0, v148
	v_add_f32_e32 v207, 1.0, v149
	v_fma_f32 v200, v200, v204, v100
	v_fma_f32 v201, v201, v205, v101
	v_fma_f32 v202, v202, v206, v102
	v_fma_f32 v203, v203, v207, v103
	v_cvt_pk_bf16_f32 v210, v200, v201
	v_cvt_pk_bf16_f32 v211, v202, v203
	global_store_dwordx2 v228, v[210:211], s[30:31] offset:512
	v_mul_f32_e32 v200, v8, v246
	v_mul_f32_e32 v201, v9, v246
	v_mul_f32_e32 v202, v10, v246
	v_mul_f32_e32 v203, v11, v246
	s_waitcnt vmcnt(15)
	v_mul_f32_e32 v200, v200, v72
	v_mul_f32_e32 v201, v201, v73
	v_mul_f32_e32 v202, v202, v74
	v_mul_f32_e32 v203, v203, v75
	v_add_f32_e32 v204, 1.0, v150
	v_add_f32_e32 v205, 1.0, v151
	v_add_f32_e32 v206, 1.0, v152
	v_add_f32_e32 v207, 1.0, v153
	v_fma_f32 v200, v200, v204, v104
	v_fma_f32 v201, v201, v205, v105
	v_fma_f32 v202, v202, v206, v106
	v_fma_f32 v203, v203, v207, v107
	v_cvt_pk_bf16_f32 v208, v200, v201
	v_cvt_pk_bf16_f32 v209, v202, v203
	global_store_dwordx2 v228, v[208:209], s[30:31] offset:1024
	v_mul_f32_e32 v200, v12, v246
	v_mul_f32_e32 v201, v13, v246
	v_mul_f32_e32 v202, v14, v246
	v_mul_f32_e32 v203, v15, v246
	s_waitcnt vmcnt(12)
	v_mul_f32_e32 v200, v200, v76
	v_mul_f32_e32 v201, v201, v77
	v_mul_f32_e32 v202, v202, v78
	v_mul_f32_e32 v203, v203, v79
	v_add_f32_e32 v204, 1.0, v154
	v_add_f32_e32 v205, 1.0, v155
	v_add_f32_e32 v206, 1.0, v156
	v_add_f32_e32 v207, 1.0, v157
	v_fma_f32 v200, v200, v204, v108
	v_fma_f32 v201, v201, v205, v109
	v_fma_f32 v202, v202, v206, v110
	v_fma_f32 v203, v203, v207, v111
	v_cvt_pk_bf16_f32 v210, v200, v201
	v_cvt_pk_bf16_f32 v211, v202, v203
	global_store_dwordx2 v228, v[210:211], s[30:31] offset:1536
	v_mul_f32_e32 v200, v16, v246
	v_mul_f32_e32 v201, v17, v246
	v_mul_f32_e32 v202, v18, v246
	v_mul_f32_e32 v203, v19, v246
	s_waitcnt vmcnt(9)
	v_mul_f32_e32 v200, v200, v80
	v_mul_f32_e32 v201, v201, v81
	v_mul_f32_e32 v202, v202, v82
	v_mul_f32_e32 v203, v203, v83
	v_add_f32_e32 v204, 1.0, v184
	v_add_f32_e32 v205, 1.0, v185
	v_add_f32_e32 v206, 1.0, v186
	v_add_f32_e32 v207, 1.0, v187
	v_fma_f32 v200, v200, v204, v112
	v_fma_f32 v201, v201, v205, v113
	v_fma_f32 v202, v202, v206, v114
	v_fma_f32 v203, v203, v207, v115
	v_cvt_pk_bf16_f32 v208, v200, v201
	v_cvt_pk_bf16_f32 v209, v202, v203
	global_store_dwordx2 v228, v[208:209], s[30:31] offset:2048
	v_mul_f32_e32 v200, v20, v246
	v_mul_f32_e32 v201, v21, v246
	v_mul_f32_e32 v202, v22, v246
	v_mul_f32_e32 v203, v23, v246
	s_waitcnt vmcnt(6)
	v_mul_f32_e32 v200, v200, v84
	v_mul_f32_e32 v201, v201, v85
	v_mul_f32_e32 v202, v202, v86
	v_mul_f32_e32 v203, v203, v87
	v_add_f32_e32 v204, 1.0, v188
	v_add_f32_e32 v205, 1.0, v189
	v_add_f32_e32 v206, 1.0, v190
	v_add_f32_e32 v207, 1.0, v191
	v_fma_f32 v200, v200, v204, v116
	v_fma_f32 v201, v201, v205, v117
	v_fma_f32 v202, v202, v206, v118
	v_fma_f32 v203, v203, v207, v119
	v_cvt_pk_bf16_f32 v210, v200, v201
	v_cvt_pk_bf16_f32 v211, v202, v203
	global_store_dwordx2 v228, v[210:211], s[30:31] offset:2560
	v_mul_f32_e32 v200, v24, v246
	v_mul_f32_e32 v201, v25, v246
	v_mul_f32_e32 v202, v26, v246
	v_mul_f32_e32 v203, v27, v246
	s_waitcnt vmcnt(3)
	v_mul_f32_e32 v200, v200, v88
	v_mul_f32_e32 v201, v201, v89
	v_mul_f32_e32 v202, v202, v90
	v_mul_f32_e32 v203, v203, v91
	v_add_f32_e32 v204, 1.0, v192
	v_add_f32_e32 v205, 1.0, v193
	v_add_f32_e32 v206, 1.0, v194
	v_add_f32_e32 v207, 1.0, v195
	v_fma_f32 v200, v200, v204, v120
	v_fma_f32 v201, v201, v205, v121
	v_fma_f32 v202, v202, v206, v122
	v_fma_f32 v203, v203, v207, v123
	v_cvt_pk_bf16_f32 v208, v200, v201
	v_cvt_pk_bf16_f32 v209, v202, v203
	global_store_dwordx2 v228, v[208:209], s[30:31] offset:3072
	v_mul_f32_e32 v200, v28, v246
	v_mul_f32_e32 v201, v29, v246
	v_mul_f32_e32 v202, v30, v246
	v_mul_f32_e32 v203, v31, v246
	s_waitcnt vmcnt(0)
; DI void post_phase(const P& p, int l, unsigned char* smem, int t0, int t1, int bstart, int bstride) {
;     ...
;             for (int i = 0; i < 8; ++i) {
;                 const int j = i * 256 + lane * 4;
;                 const f32x4 gw = *(const f32x4*)(p.norm_pre + DM + j), sh = *(const f32x4*)(md1 + j), scl = *(const f32x4*)(md1 + 2048 + j);
;                 float o[4];
; #pragma unroll
;                 for (int e = 0; e < 4; ++e) o[e] = y[i][e] * rstd2 * gw[e] * (1.f + scl[e]) + sh[e];
;                 u32x2 w; w.x = pk2(o[0], o[1]); w.y = pk2(o[2], o[3]);
;                 *(u32x2*)(nb + (size_t)row * DM + j) = w;
;             }
;         }
;       }
;       if (l == 0) { asm volatile("s_waitcnt vmcnt(0)" ::: "memory"); __syncthreads(); skinny_tile(p, 1, rt * 16, (float*)smem); }
	v_mul_f32_e32 v200, v200, v92
	v_mul_f32_e32 v201, v201, v93
	v_mul_f32_e32 v202, v202, v94
	v_mul_f32_e32 v203, v203, v95
	v_add_f32_e32 v204, 1.0, v196
	v_add_f32_e32 v205, 1.0, v197
	v_add_f32_e32 v206, 1.0, v198
	v_add_f32_e32 v207, 1.0, v199
	v_fma_f32 v200, v200, v204, v124
	v_fma_f32 v201, v201, v205, v125
	v_fma_f32 v202, v202, v206, v126
	v_fma_f32 v203, v203, v207, v127
	v_cvt_pk_bf16_f32 v210, v200, v201
	v_cvt_pk_bf16_f32 v211, v202, v203
	global_store_dwordx2 v228, v[210:211], s[30:31] offset:3584
	v_mul_f32_e32 v200, v32, v247
	v_mul_f32_e32 v201, v33, v247
	v_mul_f32_e32 v202, v34, v247
	v_mul_f32_e32 v203, v35, v247
	v_mul_f32_e32 v200, v200, v64
	v_mul_f32_e32 v201, v201, v65
	v_mul_f32_e32 v202, v202, v66
	v_mul_f32_e32 v203, v203, v67
	v_add_f32_e32 v204, 1.0, v142
	v_add_f32_e32 v205, 1.0, v143
	v_add_f32_e32 v206, 1.0, v144
	v_add_f32_e32 v207, 1.0, v145
	v_fma_f32 v200, v200, v204, v96
	v_fma_f32 v201, v201, v205, v97
	v_fma_f32 v202, v202, v206, v98
	v_fma_f32 v203, v203, v207, v99
	v_cvt_pk_bf16_f32 v208, v200, v201
	v_cvt_pk_bf16_f32 v209, v202, v203
	global_store_dwordx2 v229, v[208:209], s[30:31] offset:0
	v_mul_f32_e32 v200, v36, v247
	v_mul_f32_e32 v201, v37, v247
	v_mul_f32_e32 v202, v38, v247
	v_mul_f32_e32 v203, v39, v247
	v_mul_f32_e32 v200, v200, v68
	v_mul_f32_e32 v201, v201, v69
	v_mul_f32_e32 v202, v202, v70
	v_mul_f32_e32 v203, v203, v71
	v_add_f32_e32 v204, 1.0, v146
	v_add_f32_e32 v205, 1.0, v147
	v_add_f32_e32 v206, 1.0, v148
	v_add_f32_e32 v207, 1.0, v149
	v_fma_f32 v200, v200, v204, v100
	v_fma_f32 v201, v201, v205, v101
	v_fma_f32 v202, v202, v206, v102
	v_fma_f32 v203, v203, v207, v103
	v_cvt_pk_bf16_f32 v210, v200, v201
	v_cvt_pk_bf16_f32 v211, v202, v203
	global_store_dwordx2 v229, v[210:211], s[30:31] offset:512
	v_mul_f32_e32 v200, v40, v247
	v_mul_f32_e32 v201, v41, v247
	v_mul_f32_e32 v202, v42, v247
	v_mul_f32_e32 v203, v43, v247
	v_mul_f32_e32 v200, v200, v72
	v_mul_f32_e32 v201, v201, v73
	v_mul_f32_e32 v202, v202, v74
	v_mul_f32_e32 v203, v203, v75
	v_add_f32_e32 v204, 1.0, v150
	v_add_f32_e32 v205, 1.0, v151
	v_add_f32_e32 v206, 1.0, v152
	v_add_f32_e32 v207, 1.0, v153
	v_fma_f32 v200, v200, v204, v104
	v_fma_f32 v201, v201, v205, v105
	v_fma_f32 v202, v202, v206, v106
	v_fma_f32 v203, v203, v207, v107
	v_cvt_pk_bf16_f32 v208, v200, v201
	v_cvt_pk_bf16_f32 v209, v202, v203
	global_store_dwordx2 v229, v[208:209], s[30:31] offset:1024
	v_mul_f32_e32 v200, v44, v247
	v_mul_f32_e32 v201, v45, v247
	v_mul_f32_e32 v202, v46, v247
	v_mul_f32_e32 v203, v47, v247
	v_mul_f32_e32 v200, v200, v76
	v_mul_f32_e32 v201, v201, v77
	v_mul_f32_e32 v202, v202, v78
	v_mul_f32_e32 v203, v203, v79
	v_add_f32_e32 v204, 1.0, v154
	v_add_f32_e32 v205, 1.0, v155
	v_add_f32_e32 v206, 1.0, v156
	v_add_f32_e32 v207, 1.0, v157
	v_fma_f32 v200, v200, v204, v108
	v_fma_f32 v201, v201, v205, v109
	v_fma_f32 v202, v202, v206, v110
	v_fma_f32 v203, v203, v207, v111
	v_cvt_pk_bf16_f32 v210, v200, v201
	v_cvt_pk_bf16_f32 v211, v202, v203
	global_store_dwordx2 v229, v[210:211], s[30:31] offset:1536
	v_mul_f32_e32 v200, v48, v247
	v_mul_f32_e32 v201, v49, v247
	v_mul_f32_e32 v202, v50, v247
	v_mul_f32_e32 v203, v51, v247
	v_mul_f32_e32 v200, v200, v80
	v_mul_f32_e32 v201, v201, v81
	v_mul_f32_e32 v202, v202, v82
	v_mul_f32_e32 v203, v203, v83
	v_add_f32_e32 v204, 1.0, v184
	v_add_f32_e32 v205, 1.0, v185
	v_add_f32_e32 v206, 1.0, v186
	v_add_f32_e32 v207, 1.0, v187
	v_fma_f32 v200, v200, v204, v112
	v_fma_f32 v201, v201, v205, v113
	v_fma_f32 v202, v202, v206, v114
	v_fma_f32 v203, v203, v207, v115
	v_cvt_pk_bf16_f32 v208, v200, v201
	v_cvt_pk_bf16_f32 v209, v202, v203
	global_store_dwordx2 v229, v[208:209], s[30:31] offset:2048
	v_mul_f32_e32 v200, v52, v247
	v_mul_f32_e32 v201, v53, v247
	v_mul_f32_e32 v202, v54, v247
	v_mul_f32_e32 v203, v55, v247
	v_mul_f32_e32 v200, v200, v84
	v_mul_f32_e32 v201, v201, v85
	v_mul_f32_e32 v202, v202, v86
	v_mul_f32_e32 v203, v203, v87
	v_add_f32_e32 v204, 1.0, v188
	v_add_f32_e32 v205, 1.0, v189
	v_add_f32_e32 v206, 1.0, v190
	v_add_f32_e32 v207, 1.0, v191
	v_fma_f32 v200, v200, v204, v116
	v_fma_f32 v201, v201, v205, v117
	v_fma_f32 v202, v202, v206, v118
	v_fma_f32 v203, v203, v207, v119
	v_cvt_pk_bf16_f32 v210, v200, v201
	v_cvt_pk_bf16_f32 v211, v202, v203
	global_store_dwordx2 v229, v[210:211], s[30:31] offset:2560
	v_mul_f32_e32 v200, v56, v247
	v_mul_f32_e32 v201, v57, v247
	v_mul_f32_e32 v202, v58, v247
	v_mul_f32_e32 v203, v59, v247
	v_mul_f32_e32 v200, v200, v88
	v_mul_f32_e32 v201, v201, v89
	v_mul_f32_e32 v202, v202, v90
	v_mul_f32_e32 v203, v203, v91
	v_add_f32_e32 v204, 1.0, v192
	v_add_f32_e32 v205, 1.0, v193
	v_add_f32_e32 v206, 1.0, v194
	v_add_f32_e32 v207, 1.0, v195
	v_fma_f32 v200, v200, v204, v120
	v_fma_f32 v201, v201, v205, v121
	v_fma_f32 v202, v202, v206, v122
	v_fma_f32 v203, v203, v207, v123
	v_cvt_pk_bf16_f32 v208, v200, v201
	v_cvt_pk_bf16_f32 v209, v202, v203
	global_store_dwordx2 v229, v[208:209], s[30:31] offset:3072
	v_mul_f32_e32 v200, v60, v247
	v_mul_f32_e32 v201, v61, v247
	v_mul_f32_e32 v202, v62, v247
	v_mul_f32_e32 v203, v63, v247
	v_mul_f32_e32 v200, v200, v92
	v_mul_f32_e32 v201, v201, v93
	v_mul_f32_e32 v202, v202, v94
	v_mul_f32_e32 v203, v203, v95
	v_add_f32_e32 v204, 1.0, v196
	v_add_f32_e32 v205, 1.0, v197
	v_add_f32_e32 v206, 1.0, v198
	v_add_f32_e32 v207, 1.0, v199
	v_fma_f32 v200, v200, v204, v124
	v_fma_f32 v201, v201, v205, v125
	v_fma_f32 v202, v202, v206, v126
	v_fma_f32 v203, v203, v207, v127
	v_cvt_pk_bf16_f32 v210, v200, v201
	v_cvt_pk_bf16_f32 v211, v202, v203
	global_store_dwordx2 v229, v[210:211], s[30:31] offset:3584
	s_lshl_b32 s36, s98, 16
	s_add_u32 s36, s36, 0x483c000
	s_add_u32 s36, s0, s36
	s_addc_u32 s37, s1, 0
	s_waitcnt vmcnt(0)
	s_barrier
; DI f32x4 mfma16(bf16x8 a, bf16x8 b, f32x4 c) { return __builtin_amdgcn_mfma_f32_16x16x32_bf16(a, b, c, 0, 0, 0); }
; DI int otid() { int t = threadIdx.x; asm volatile("" : "+v"(t)); return t; }
; DI void skinny_tile(const P& p, int l, int r0, float* red) {
;     const bf16_t* A = (const bf16_t*)(p.ws + WS_NBUF);
;     const bf16_t* Bt = (const bf16_t*)(p.ws + WS_WNT) + (size_t)l * NNAR * DM;
;     float* G = (float*)(p.ws + WS_G);
;     const int tid = otid(), w = tid >> 6, lane = tid & 63, l15 = lane & 15, g = lane >> 4;
;     f32x4 acc[3];
; #pragma unroll
;     for (int n = 0; n < 3; ++n) acc[n] = (f32x4){0.f, 0.f, 0.f, 0.f};
;     const bf16_t* ap = A + (size_t)(r0 + l15) * DM + 256 * w + 8 * g;
;     const bf16_t* bp = Bt + (size_t)l15 * DM + 256 * w + 8 * g;
; #pragma unroll
;     for (int ks = 0; ks < 8; ++ks) {
;         const bf16x8 a0 = *(const bf16x8*)(ap + 32 * ks);
; #pragma unroll
;         for (int n = 0; n < 3; ++n) acc[n] = mfma16(a0, *(const bf16x8*)(bp + (size_t)16 * n * DM + 32 * ks), acc[n]);
;     }
; #pragma unroll
;     for (int n = 0; n < 3; ++n)
; #pragma unroll
;         for (int r = 0; r < 4; ++r) red[w * 768 + (4 * g + r) * 48 + 16 * n + l15] = acc[n][r];
;     __syncthreads();
;     for (int e = tid; e < 768; e += 512) {
;         float sum = 0.f;
; #pragma unroll
;         for (int k = 0; k < 8; ++k) sum += red[k * 768 + e];
;         G[(size_t)r0 * NNAR + e] = sum;
;     }
;     __syncthreads();
; DI void post_phase(const P& p, int l, unsigned char* smem, int t0, int t1, int bstart, int bstride) {
;     ...
;       if (l == 0) { asm volatile("s_waitcnt vmcnt(0)" ::: "memory"); __syncthreads(); skinny_tile(p, 1, rt * 16, (float*)smem); }
	global_load_dwordx4 v[0:3], v212, s[36:37] offset:0
	global_load_dwordx4 v[32:35], v212, s[6:7] offset:0
	global_load_dwordx4 v[36:39], v213, s[6:7] offset:0
	global_load_dwordx4 v[40:43], v214, s[6:7] offset:0
	global_load_dwordx4 v[4:7], v212, s[36:37] offset:64
	global_load_dwordx4 v[44:47], v212, s[6:7] offset:64
	global_load_dwordx4 v[48:51], v213, s[6:7] offset:64
	global_load_dwordx4 v[52:55], v214, s[6:7] offset:64
	global_load_dwordx4 v[8:11], v212, s[36:37] offset:128
	global_load_dwordx4 v[56:59], v212, s[6:7] offset:128
	global_load_dwordx4 v[60:63], v213, s[6:7] offset:128
	global_load_dwordx4 v[64:67], v214, s[6:7] offset:128
	global_load_dwordx4 v[12:15], v212, s[36:37] offset:192
	global_load_dwordx4 v[68:71], v212, s[6:7] offset:192
	global_load_dwordx4 v[72:75], v213, s[6:7] offset:192
	global_load_dwordx4 v[76:79], v214, s[6:7] offset:192
	global_load_dwordx4 v[16:19], v212, s[36:37] offset:256
	global_load_dwordx4 v[80:83], v212, s[6:7] offset:256
	global_load_dwordx4 v[84:87], v213, s[6:7] offset:256
	global_load_dwordx4 v[88:91], v214, s[6:7] offset:256
	global_load_dwordx4 v[20:23], v212, s[36:37] offset:320
	global_load_dwordx4 v[92:95], v212, s[6:7] offset:320
	global_load_dwordx4 v[96:99], v213, s[6:7] offset:320
	global_load_dwordx4 v[100:103], v214, s[6:7] offset:320
	global_load_dwordx4 v[24:27], v212, s[36:37] offset:384
	global_load_dwordx4 v[104:107], v212, s[6:7] offset:384
	global_load_dwordx4 v[108:111], v213, s[6:7] offset:384
	global_load_dwordx4 v[112:115], v214, s[6:7] offset:384
	global_load_dwordx4 v[28:31], v212, s[36:37] offset:448
	global_load_dwordx4 v[116:119], v212, s[6:7] offset:448
	global_load_dwordx4 v[120:123], v213, s[6:7] offset:448
	global_load_dwordx4 v[124:127], v214, s[6:7] offset:448
	s_waitcnt vmcnt(30)
	v_mfma_f32_16x16x32_bf16 v[142:145], v[0:3], v[32:35], 0
	s_waitcnt vmcnt(29)
	v_mfma_f32_16x16x32_bf16 v[146:149], v[0:3], v[36:39], 0
	s_waitcnt vmcnt(28)
	v_mfma_f32_16x16x32_bf16 v[150:153], v[0:3], v[40:43], 0
	s_waitcnt vmcnt(26)
	v_mfma_f32_16x16x32_bf16 v[142:145], v[4:7], v[44:47], v[142:145]
	s_waitcnt vmcnt(25)
	v_mfma_f32_16x16x32_bf16 v[146:149], v[4:7], v[48:51], v[146:149]
	s_waitcnt vmcnt(24)
	v_mfma_f32_16x16x32_bf16 v[150:153], v[4:7], v[52:55], v[150:153]
	s_waitcnt vmcnt(22)
	v_mfma_f32_16x16x32_bf16 v[142:145], v[8:11], v[56:59], v[142:145]
	s_waitcnt vmcnt(21)
	v_mfma_f32_16x16x32_bf16 v[146:149], v[8:11], v[60:63], v[146:149]
	s_waitcnt vmcnt(20)
	v_mfma_f32_16x16x32_bf16 v[150:153], v[8:11], v[64:67], v[150:153]
	s_waitcnt vmcnt(18)
	v_mfma_f32_16x16x32_bf16 v[142:145], v[12:15], v[68:71], v[142:145]
	s_waitcnt vmcnt(17)
	v_mfma_f32_16x16x32_bf16 v[146:149], v[12:15], v[72:75], v[146:149]
	s_waitcnt vmcnt(16)
	v_mfma_f32_16x16x32_bf16 v[150:153], v[12:15], v[76:79], v[150:153]
	s_waitcnt vmcnt(14)
	v_mfma_f32_16x16x32_bf16 v[142:145], v[16:19], v[80:83], v[142:145]
	s_waitcnt vmcnt(13)
	v_mfma_f32_16x16x32_bf16 v[146:149], v[16:19], v[84:87], v[146:149]
	s_waitcnt vmcnt(12)
	v_mfma_f32_16x16x32_bf16 v[150:153], v[16:19], v[88:91], v[150:153]
	s_waitcnt vmcnt(10)
	v_mfma_f32_16x16x32_bf16 v[142:145], v[20:23], v[92:95], v[142:145]
	s_waitcnt vmcnt(9)
	v_mfma_f32_16x16x32_bf16 v[146:149], v[20:23], v[96:99], v[146:149]
	s_waitcnt vmcnt(8)
	v_mfma_f32_16x16x32_bf16 v[150:153], v[20:23], v[100:103], v[150:153]
	s_waitcnt vmcnt(6)
	v_mfma_f32_16x16x32_bf16 v[142:145], v[24:27], v[104:107], v[142:145]
	s_waitcnt vmcnt(5)
	v_mfma_f32_16x16x32_bf16 v[146:149], v[24:27], v[108:111], v[146:149]
	s_waitcnt vmcnt(4)
	v_mfma_f32_16x16x32_bf16 v[150:153], v[24:27], v[112:115], v[150:153]
	s_waitcnt vmcnt(2)
	v_mfma_f32_16x16x32_bf16 v[142:145], v[28:31], v[116:119], v[142:145]
	s_waitcnt vmcnt(1)
	v_mfma_f32_16x16x32_bf16 v[146:149], v[28:31], v[120:123], v[146:149]
	s_waitcnt vmcnt(0)
	v_mfma_f32_16x16x32_bf16 v[150:153], v[28:31], v[124:127], v[150:153]
	s_nop 9
	ds_write_b32 v215, v142 offset:0
	ds_write_b32 v215, v143 offset:192
	ds_write_b32 v215, v144 offset:384
	ds_write_b32 v215, v145 offset:576
	ds_write_b32 v215, v146 offset:64
	ds_write_b32 v215, v147 offset:256
	ds_write_b32 v215, v148 offset:448
	ds_write_b32 v215, v149 offset:640
	ds_write_b32 v215, v150 offset:128
	ds_write_b32 v215, v151 offset:320
	ds_write_b32 v215, v152 offset:512
	ds_write_b32 v215, v153 offset:704
	s_waitcnt lgkmcnt(0)
	s_barrier
	ds_read_b32 v184, v216 offset:0
	ds_read_b32 v185, v216 offset:3072
	ds_read_b32 v186, v216 offset:6144
	ds_read_b32 v187, v216 offset:9216
	ds_read_b32 v188, v216 offset:12288
	ds_read_b32 v189, v216 offset:15360
	ds_read_b32 v190, v216 offset:18432
	ds_read_b32 v191, v216 offset:21504
	ds_read_b32 v192, v216 offset:2048
	ds_read_b32 v193, v216 offset:5120
	ds_read_b32 v194, v216 offset:8192
	ds_read_b32 v195, v216 offset:11264
	ds_read_b32 v196, v216 offset:14336
	ds_read_b32 v197, v216 offset:17408
	ds_read_b32 v198, v216 offset:20480
	ds_read_b32 v199, v216 offset:23552
	s_mul_i32 s36, s98, 0xc00
	s_add_u32 s36, s40, s36
	s_addc_u32 s37, s41, 0
	s_waitcnt lgkmcnt(8)
	v_add_f32_e32 v217, 0, v184
	v_add_f32_e32 v217, v217, v185
	v_add_f32_e32 v217, v217, v186
	v_add_f32_e32 v217, v217, v187
	v_add_f32_e32 v217, v217, v188
	v_add_f32_e32 v217, v217, v189
	v_add_f32_e32 v217, v217, v190
	v_add_f32_e32 v217, v217, v191
	s_waitcnt lgkmcnt(0)
	v_add_f32_e32 v218, 0, v192
	v_add_f32_e32 v218, v218, v193
	v_add_f32_e32 v218, v218, v194
	v_add_f32_e32 v218, v218, v195
	v_add_f32_e32 v218, v218, v196
	v_add_f32_e32 v218, v218, v197
	v_add_f32_e32 v218, v218, v198
	v_add_f32_e32 v218, v218, v199
	global_store_dword v216, v217, s[36:37]
	v_cmp_gt_u32_e32 vcc, 0x100, v166
	s_and_saveexec_b64 s[42:43], vcc
	global_store_dword v216, v218, s[36:37] offset:2048
	s_mov_b64 exec, s[42:43]
	s_add_u32 s98, s98, s99
	s_barrier
	s_cmp_lt_u32 s98, s100
	s_cbranch_scc1 .Lpost0_tile
	s_cmp_lg_u32 s101, 0
	s_cbranch_scc1 .Lpost0_retB
